# speedup vs baseline: 1.0226x; 1.0226x over previous
.LBB0_387:
	s_ashr_i32 s0, s78, 31
	s_lshr_b32 s0, s0, 29
	s_add_i32 s0, s78, s0
	s_ashr_i32 s6, s0, 3
	s_and_b32 s0, s0, 0xfffff8
	s_sub_i32 s3, s78, s0
	s_ashr_i32 s7, s6, 31
	s_mul_i32 s11, s6, 0x2e00000
	s_mul_hi_i32 s10, s6, 0x2e00000
	s_add_u32 s0, s38, s11
	v_mov_b32_e32 v4, v228
	s_addc_u32 s1, s39, s10
	s_lshl_b32 s79, s3, 8
	v_mov_b64_e32 v[2:3], s[0:1]
	v_and_b32_e32 v6, 31, v4
	v_ashrrev_i32_e32 v5, 6, v4
	v_or_b32_e32 v0, s79, v6
	v_lshl_add_u32 v0, v5, 5, v0
	v_bfe_u32 v7, v4, 5, 1
	v_mad_i64_i32 v[2:3], s[8:9], v0, s48, v[2:3]
	v_lshl_add_u64 v[2:3], v[2:3], 0, s[14:15]
	v_lshlrev_b32_e32 v0, 4, v7
	v_lshl_add_u64 v[2:3], v[2:3], 0, v[0:1]
	v_readfirstlane_b32 s3, v5
	v_mov_b32_e32 v5, v228
	global_load_dwordx4 v[176:179], v[2:3], off
	global_load_dwordx4 v[180:183], v[2:3], off offset:32
	global_load_dwordx4 v[184:187], v[2:3], off offset:64
	global_load_dwordx4 v[188:191], v[2:3], off offset:96
	global_load_dwordx4 v[192:195], v[2:3], off offset:128
	global_load_dwordx4 v[196:199], v[2:3], off offset:160
	global_load_dwordx4 v[200:203], v[2:3], off offset:192
	global_load_dwordx4 v[204:207], v[2:3], off offset:224
	s_barrier
	s_add_u32 s0, s0, s14
	v_and_b32_e32 v3, 0x60, v5
	v_lshlrev_b32_e32 v9, 3, v5
	v_bfe_u32 v2, v5, 2, 2
	v_and_or_b32 v9, v9, 24, v3
	v_lshrrev_b32_e32 v3, 1, v5
	v_and_b32_e32 v8, 15, v5
	v_and_or_b32 v10, v3, 8, v2
	v_ashrrev_i32_e32 v3, 4, v5
	v_bitop3_b32 v2, v3, v8, 7 bitop3:0x6c
	v_mul_lo_u32 v11, v3, s48
	v_lshl_or_b32 v2, v2, 4, v11
	v_and_b32_e32 v11, 0x7ffff0, v3
	v_lshrrev_b32_e32 v3, 1, v3
	v_and_b32_e32 v3, 4, v3
	s_addc_u32 s1, s1, s15
	v_or3_b32 v3, v11, v3, v10
	s_add_u32 s8, s0, 0x1000
	v_mul_u32_u24_e32 v3, 0x2e00, v3
	s_addc_u32 s9, s1, 0
	s_lshl_b32 s24, s3, 10
	v_or_b32_e32 v3, v3, v9
	s_add_i32 s80, s24, 0
	v_lshlrev_b32_e32 v11, 1, v3
	v_mov_b32_e32 v3, v1
	s_add_i32 s81, s80, 0x10000
	v_lshl_add_u64 v[2:3], s[0:1], 0, v[2:3]
	v_lshl_add_u64 v[2:3], v[2:3], 0, s[16:17]
	s_mov_b32 m0, s81
	v_mov_b32_e32 v14, v1
	global_load_lds_dwordx4 v[2:3], off
	v_add_u32_e32 v2, 0x200, v5
	v_ashrrev_i32_e32 v3, 4, v2
	v_bitop3_b32 v2, v3, v8, 7 bitop3:0x6c
	v_mul_lo_u32 v5, v3, s48
	v_lshl_or_b32 v2, v2, 4, v5
	v_and_b32_e32 v5, 0x7ffff0, v3
	v_lshrrev_b32_e32 v3, 1, v3
	v_and_b32_e32 v3, 4, v3
	v_or3_b32 v3, v5, v3, v10
	v_mul_u32_u24_e32 v3, 0x2e00, v3
	v_or_b32_e32 v3, v3, v9
	v_lshlrev_b32_e32 v5, 1, v3
	v_mov_b32_e32 v3, v1
	s_mov_b32 m0, s80
	v_lshl_add_u64 v[2:3], s[0:1], 0, v[2:3]
	global_load_lds_dwordx4 v11, s[8:9]
	v_lshl_add_u64 v[2:3], v[2:3], 0, s[16:17]
	s_add_i32 m0, s80, 0x12000
	v_mov_b32_e32 v15, v1
	global_load_lds_dwordx4 v[2:3], off
	s_add_i32 m0, s80, 0x2000
	v_mov_b32_e32 v2, v228
	global_load_lds_dwordx4 v5, s[8:9]
	s_cmp_lg_u32 0, -1
	v_and_b32_e32 v8, 0x60, v2
	v_lshlrev_b32_e32 v9, 3, v2
	v_bfe_u32 v5, v2, 2, 2
	v_and_or_b32 v8, v9, 24, v8
	v_lshrrev_b32_e32 v9, 1, v2
	v_and_b32_e32 v3, 15, v2
	v_and_or_b32 v5, v9, 8, v5
	v_ashrrev_i32_e32 v9, 4, v2
	s_cselect_b32 s24, 0, 0
	v_bitop3_b32 v10, v9, v3, 7 bitop3:0x6c
	v_mul_lo_u32 v11, v9, s48
	s_add_i32 s27, s24, 0x10000
	v_lshl_or_b32 v10, v10, 4, v11
	v_and_b32_e32 v11, 0x7ffff0, v9
	v_lshrrev_b32_e32 v9, 1, v9
	s_add_u32 s8, s0, 0x170800
	v_and_b32_e32 v9, 4, v9
	s_addc_u32 s9, s1, 0
	v_or3_b32 v9, v11, v9, v5
	s_add_u32 s0, s0, 0x171000
	v_mul_u32_u24_e32 v9, 0x2e00, v9
	s_addc_u32 s1, s1, 0
	s_add_i32 m0, s80, 0x14000
	s_add_i32 s33, s80, 0x4000
	v_or_b32_e32 v9, v9, v8
	v_add_u32_e32 v2, 0x200, v2
	v_lshlrev_b32_e32 v9, 1, v9
	global_load_lds_dwordx4 v10, s[8:9]
	s_mov_b32 m0, s33
	v_ashrrev_i32_e32 v2, 4, v2
	global_load_lds_dwordx4 v9, s[0:1]
	v_bitop3_b32 v3, v2, v3, 7 bitop3:0x6c
	v_mul_lo_u32 v9, v2, s48
	v_lshl_or_b32 v3, v3, 4, v9
	v_and_b32_e32 v9, 0x7ffff0, v2
	v_lshrrev_b32_e32 v2, 1, v2
	v_and_b32_e32 v2, 4, v2
	v_or3_b32 v2, v9, v2, v5
	v_mul_u32_u24_e32 v2, 0x2e00, v2
	v_or_b32_e32 v2, v2, v8
	s_add_i32 m0, s80, 0x16000
	v_lshlrev_b32_e32 v2, 1, v2
	global_load_lds_dwordx4 v3, s[8:9]
	s_add_i32 m0, s80, 0x6000
	v_and_b32_e32 v3, 63, v4
	global_load_lds_dwordx4 v2, s[0:1]
	v_lshlrev_b32_e32 v8, 4, v4
	v_lshlrev_b32_e32 v5, 3, v3
	v_and_b32_e32 v8, 0xc0, v8
	v_lshlrev_b32_e32 v9, 1, v4
	v_and_b32_e32 v2, 0x3fffffc0, v4
	v_and_or_b32 v8, v5, 24, v8
	v_and_b32_e32 v9, 32, v9
	v_and_b32_e32 v5, 0x100, v5
	v_lshlrev_b32_e32 v5, 3, v5
	v_bitop3_b32 v4, v7, v4, 7 bitop3:0x78
	s_cmp_gt_i32 s3, 3
	v_lshl_add_u32 v2, v2, 2, s31
	v_or3_b32 v232, v8, v9, v5
	v_lshlrev_b32_e32 v5, 8, v6
	v_lshlrev_b32_e32 v4, 4, v4
	s_cselect_b64 s[34:35], -1, 0
	s_cmp_lt_i32 s3, 4
	v_add3_u32 v233, v5, s27, v4
	s_cselect_b64 s[46:47], -1, 0
	v_cmp_gt_u32_e64 s[8:9], 32, v3
	v_lshl_add_u32 v235, v6, 2, v2
	v_add_u32_e32 v236, v2, v0
	s_add_u32 s84, s25, s11
	v_mov_b32_e32 v0, v1
	v_mov_b32_e32 v2, v1
	v_mov_b32_e32 v3, v1
	v_mov_b32_e32 v4, v1
	v_mov_b32_e32 v5, v1
	v_mov_b32_e32 v6, v1
	v_mov_b32_e32 v7, v1
	v_mov_b32_e32 v8, v1
	v_mov_b32_e32 v9, v1
	v_mov_b32_e32 v10, v1
	v_mov_b32_e32 v11, v1
	v_mov_b32_e32 v12, v1
	v_mov_b32_e32 v13, v1
	v_mov_b64_e32 v[110:111], v[14:15]
	v_mov_b64_e32 v[94:95], v[14:15]
	v_mov_b64_e32 v[46:47], v[14:15]
	v_mov_b64_e32 v[30:31], v[14:15]
	v_mov_b64_e32 v[142:143], v[14:15]
	v_mov_b64_e32 v[126:127], v[14:15]
	v_mov_b64_e32 v[78:79], v[14:15]
	v_mov_b64_e32 v[62:63], v[14:15]
	v_add_u32_e32 v234, s24, v232
	s_addc_u32 s85, s30, s10
	s_mov_b64 s[56:57], 0
	s_xor_b64 s[76:77], s[34:35], -1
	s_mov_b32 s86, 0
	v_mov_b64_e32 v[108:109], v[12:13]
	v_mov_b64_e32 v[106:107], v[10:11]
	v_mov_b64_e32 v[104:105], v[8:9]
	v_mov_b64_e32 v[102:103], v[6:7]
	v_mov_b64_e32 v[100:101], v[4:5]
	v_mov_b64_e32 v[98:99], v[2:3]
	v_mov_b64_e32 v[96:97], v[0:1]
	v_mov_b64_e32 v[92:93], v[12:13]
	v_mov_b64_e32 v[90:91], v[10:11]
	v_mov_b64_e32 v[88:89], v[8:9]
	v_mov_b64_e32 v[86:87], v[6:7]
	v_mov_b64_e32 v[84:85], v[4:5]
	v_mov_b64_e32 v[82:83], v[2:3]
	v_mov_b64_e32 v[80:81], v[0:1]
	v_mov_b64_e32 v[44:45], v[12:13]
	v_mov_b64_e32 v[42:43], v[10:11]
	v_mov_b64_e32 v[40:41], v[8:9]
	v_mov_b64_e32 v[38:39], v[6:7]
	v_mov_b64_e32 v[36:37], v[4:5]
	v_mov_b64_e32 v[34:35], v[2:3]
	v_mov_b64_e32 v[32:33], v[0:1]
	v_mov_b64_e32 v[28:29], v[12:13]
	v_mov_b64_e32 v[26:27], v[10:11]
	v_mov_b64_e32 v[24:25], v[8:9]
	v_mov_b64_e32 v[22:23], v[6:7]
	v_mov_b64_e32 v[20:21], v[4:5]
	v_mov_b64_e32 v[18:19], v[2:3]
	v_mov_b64_e32 v[16:17], v[0:1]
	v_mov_b64_e32 v[140:141], v[12:13]
	v_mov_b64_e32 v[138:139], v[10:11]
	v_mov_b64_e32 v[136:137], v[8:9]
	v_mov_b64_e32 v[134:135], v[6:7]
	v_mov_b64_e32 v[132:133], v[4:5]
	v_mov_b64_e32 v[130:131], v[2:3]
	v_mov_b64_e32 v[128:129], v[0:1]
	v_mov_b64_e32 v[124:125], v[12:13]
	v_mov_b64_e32 v[122:123], v[10:11]
	v_mov_b64_e32 v[120:121], v[8:9]
	v_mov_b64_e32 v[118:119], v[6:7]
	v_mov_b64_e32 v[116:117], v[4:5]
	v_mov_b64_e32 v[114:115], v[2:3]
	v_mov_b64_e32 v[112:113], v[0:1]
	v_mov_b64_e32 v[76:77], v[12:13]
	v_mov_b64_e32 v[74:75], v[10:11]
	v_mov_b64_e32 v[72:73], v[8:9]
	v_mov_b64_e32 v[70:71], v[6:7]
	v_mov_b64_e32 v[68:69], v[4:5]
	v_mov_b64_e32 v[66:67], v[2:3]
	v_mov_b64_e32 v[64:65], v[0:1]
	v_mov_b64_e32 v[60:61], v[12:13]
	v_mov_b64_e32 v[58:59], v[10:11]
	v_mov_b64_e32 v[56:57], v[8:9]
	v_mov_b64_e32 v[54:55], v[6:7]
	v_mov_b64_e32 v[52:53], v[4:5]
	v_mov_b64_e32 v[50:51], v[2:3]
	v_mov_b64_e32 v[48:49], v[0:1]
	s_mov_b32 s87, 0
	v_mov_b32_e32 v237, v1
	v_mov_b32_e32 v238, v1
	v_mov_b32_e32 v208, v1
	v_mov_b32_e32 v209, v1
	v_mov_b32_e32 v210, v1
	v_mov_b32_e32 v211, v1
	v_lshrrev_b32_e32 v250, 4, v228
	v_and_b32_e32 v251, 15, v228
	v_and_b32_e32 v252, 7, v250
	v_xor_b32_e32 v251, v251, v252
	v_mul_u32_u24_e32 v250, 0x5c00, v250
	v_lshl_or_b32 v250, v251, 4, v250
	v_bfe_u32 v251, v228, 2, 2
	v_bfe_u32 v252, v228, 7, 1
	v_lshl_or_b32 v251, v252, 2, v251
	v_bfe_u32 v252, v228, 4, 1
	v_lshl_or_b32 v251, v252, 3, v251
	v_bfe_u32 v252, v228, 8, 1
	v_lshl_or_b32 v251, v252, 4, v251
	v_mul_u32_u24_e32 v251, 0x5c00, v251
	v_bfe_u32 v252, v228, 5, 2
	v_lshl_or_b32 v251, v252, 6, v251
	v_and_b32_e32 v252, 3, v228
	v_lshl_or_b32 v251, v252, 4, v251
	s_waitcnt vmcnt(0)
	s_branch .LBB0_389

.LBB0_393:
	s_barrier
	s_cmp_gt_u32 s87, 29
	s_cbranch_scc1 .LBB0_395
	s_add_i32 s3, s86, 0x8000
	s_and_b32 s3, s3, 0xc000
	s_add_u32 s0, s84, s56
	s_addc_u32 s1, s85, s57
	s_add_u32 s10, s0, s40
	s_addc_u32 s11, s1, s41
	s_add_u32 s0, s0, s18
	s_addc_u32 s1, s1, s19
	s_add_i32 m0, s81, s3
	s_nop 0
	global_load_lds_dwordx4 v250, s[0:1]
	s_add_i32 m0, s80, s3
	s_add_i32 s3, s3, 0x2000
	global_load_lds_dwordx4 v251, s[10:11]
	s_add_u32 s0, s0, 0xb8000
	s_addc_u32 s1, s1, 0
	s_add_i32 m0, s81, s3
	s_add_u32 s10, s10, 0xb8000
	s_addc_u32 s11, s11, 0
	global_load_lds_dwordx4 v250, s[0:1]
	s_add_i32 m0, s80, s3
	s_nop 0
	global_load_lds_dwordx4 v251, s[10:11]
.LBB0_395:
	s_cmp_eq_u32 s56, 0
	s_cselect_b64 s[0:1], -1, 0
	s_or_b64 s[0:1], s[76:77], s[0:1]
	s_and_b64 vcc, exec, s[0:1]
	s_cbranch_vccnz .LBB0_397
	s_add_i32 s0, s86, 0xc000
	s_and_b32 s0, s0, 0xc000
	v_add_u32_e32 v0, s0, v234
	ds_read_b64_tr_b16 v[144:145], v0 offset:0x2000
	ds_read_b64_tr_b16 v[146:147], v0 offset:0x2100
	ds_read_b64_tr_b16 v[148:149], v0 offset:0x3000
	ds_read_b64_tr_b16 v[150:151], v0 offset:0x3100
	ds_read_b64_tr_b16 v[152:153], v0 offset:0x2200
	ds_read_b64_tr_b16 v[154:155], v0 offset:0x2300
	ds_read_b64_tr_b16 v[156:157], v0 offset:0x3200
	ds_read_b64_tr_b16 v[158:159], v0 offset:0x3300
	ds_read_b64_tr_b16 v[160:161], v0 offset:0x2400
	ds_read_b64_tr_b16 v[162:163], v0 offset:0x2500
	ds_read_b64_tr_b16 v[164:165], v0 offset:0x3400
	ds_read_b64_tr_b16 v[166:167], v0 offset:0x3500
	s_waitcnt lgkmcnt(10)
	s_nop 0
	v_mfma_f32_32x32x16_bf16 v[128:143], v[6:9], v[144:147], v[128:143]
	v_mfma_f32_32x32x16_bf16 v[96:111], v[2:5], v[144:147], v[96:111]
	ds_read_b64_tr_b16 v[168:169], v0 offset:0x2600
	ds_read_b64_tr_b16 v[170:171], v0 offset:0x2700
	s_waitcnt lgkmcnt(10)
	v_mfma_f32_32x32x16_bf16 v[128:143], v[208:211], v[148:151], v[128:143]
	v_mfma_f32_32x32x16_bf16 v[96:111], v[10:13], v[148:151], v[96:111]
	ds_read_b64_tr_b16 v[172:173], v0 offset:0x3600
	ds_read_b64_tr_b16 v[174:175], v0 offset:0x3700
	s_waitcnt lgkmcnt(10)
	v_mfma_f32_32x32x16_bf16 v[112:127], v[6:9], v[152:155], v[112:127]
	v_mfma_f32_32x32x16_bf16 v[80:95], v[2:5], v[152:155], v[80:95]
	s_waitcnt lgkmcnt(8)
	v_mfma_f32_32x32x16_bf16 v[112:127], v[208:211], v[156:159], v[112:127]
	v_mfma_f32_32x32x16_bf16 v[80:95], v[10:13], v[156:159], v[80:95]
	s_waitcnt lgkmcnt(6)
	v_mfma_f32_32x32x16_bf16 v[64:79], v[6:9], v[160:163], v[64:79]
	v_mfma_f32_32x32x16_bf16 v[32:47], v[2:5], v[160:163], v[32:47]
	s_waitcnt lgkmcnt(4)
	v_mfma_f32_32x32x16_bf16 v[64:79], v[208:211], v[164:167], v[64:79]
	v_mfma_f32_32x32x16_bf16 v[32:47], v[10:13], v[164:167], v[32:47]
	s_waitcnt lgkmcnt(2)
	v_mfma_f32_32x32x16_bf16 v[48:63], v[6:9], v[168:171], v[48:63]
	v_mfma_f32_32x32x16_bf16 v[16:31], v[2:5], v[168:171], v[16:31]
	s_waitcnt lgkmcnt(0)
	v_mfma_f32_32x32x16_bf16 v[48:63], v[208:211], v[172:175], v[48:63]
	v_mfma_f32_32x32x16_bf16 v[16:31], v[10:13], v[172:175], v[16:31]

.LBB0_400:
	v_exp_f32_e32 v159, v175
	v_pk_add_f32 v[160:161], v[144:145], v[146:147]
	v_pk_add_f32 v[162:163], v[148:149], v[150:151]
	v_pk_add_f32 v[160:161], v[152:153], v[160:161]
	v_pk_add_f32 v[162:163], v[154:155], v[162:163]
	v_pk_add_f32 v[160:161], v[156:157], v[160:161]
	v_pk_add_f32 v[162:163], v[158:159], v[162:163]
	s_nop 0
	v_pk_add_f32 v[160:161], v[160:161], v[162:163]
	s_nop 0
	v_pk_add_f32 v[160:161], v[160:161], v[160:161] op_sel:[0,1] op_sel_hi:[1,0]
	s_nop 0
	v_cmp_lt_f32_e32 vcc, s58, v160
	v_cmp_gt_f32_e64 s[10:11], s59, v160
	s_and_b64 s[0:1], vcc, s[10:11]
	s_cmp_lg_u64 s[0:1], exec
	s_cselect_b64 vcc, -1, 0
	s_cbranch_vccnz .LBB0_402
	v_cvt_pk_bf16_f32 v216, v144, v145
	v_cvt_pk_bf16_f32 v217, v146, v147
	v_cvt_pk_bf16_f32 v218, v148, v149
	v_cvt_pk_bf16_f32 v219, v150, v151
	v_cvt_pk_bf16_f32 v224, v152, v153
	v_cvt_pk_bf16_f32 v225, v154, v155
	v_cvt_pk_bf16_f32 v226, v156, v157
	v_cvt_pk_bf16_f32 v227, v158, v159
	v_add_f32_e32 v15, v15, v160

.LBB0_406:
	v_exp_f32_e32 v159, v175
	v_pk_add_f32 v[160:161], v[144:145], v[146:147]
	v_pk_add_f32 v[162:163], v[148:149], v[150:151]
	v_pk_add_f32 v[160:161], v[152:153], v[160:161]
	v_pk_add_f32 v[162:163], v[154:155], v[162:163]
	v_pk_add_f32 v[160:161], v[156:157], v[160:161]
	v_pk_add_f32 v[162:163], v[158:159], v[162:163]
	s_nop 0
	v_pk_add_f32 v[160:161], v[160:161], v[162:163]
	s_nop 0
	v_pk_add_f32 v[160:161], v[160:161], v[160:161] op_sel:[0,1] op_sel_hi:[1,0]
	s_nop 0
	v_cmp_lt_f32_e32 vcc, s58, v160
	v_cmp_gt_f32_e64 s[10:11], s59, v160
	s_and_b64 s[0:1], vcc, s[10:11]
	s_cmp_lg_u64 s[0:1], exec
	s_cselect_b64 vcc, -1, 0
	s_cbranch_vccnz .LBB0_408
	v_cvt_pk_bf16_f32 v212, v144, v145
	v_cvt_pk_bf16_f32 v213, v146, v147
	v_cvt_pk_bf16_f32 v214, v148, v149
	v_cvt_pk_bf16_f32 v215, v150, v151
	v_cvt_pk_bf16_f32 v220, v152, v153
	v_cvt_pk_bf16_f32 v221, v154, v155
	v_cvt_pk_bf16_f32 v222, v156, v157
	v_cvt_pk_bf16_f32 v223, v158, v159
	v_add_f32_e32 v14, v14, v160

.LBB0_413:
	v_add_u32_e32 v242, s27, v234
	ds_read_b64_tr_b16 v[144:145], v242 offset:0x0
	ds_read_b64_tr_b16 v[146:147], v242 offset:0x100
	ds_read_b64_tr_b16 v[148:149], v242 offset:0x1000
	ds_read_b64_tr_b16 v[150:151], v242 offset:0x1100
	ds_read_b64_tr_b16 v[152:153], v242 offset:0x200
	ds_read_b64_tr_b16 v[154:155], v242 offset:0x300
	ds_read_b64_tr_b16 v[156:157], v242 offset:0x1200
	ds_read_b64_tr_b16 v[158:159], v242 offset:0x1300
	ds_read_b64_tr_b16 v[160:161], v242 offset:0x400
	ds_read_b64_tr_b16 v[162:163], v242 offset:0x500
	ds_read_b64_tr_b16 v[164:165], v242 offset:0x1400
	ds_read_b64_tr_b16 v[166:167], v242 offset:0x1500
	s_waitcnt lgkmcnt(10)
	s_nop 0
	v_mfma_f32_32x32x16_bf16 v[128:143], v[216:219], v[144:147], v[128:143]
	v_mfma_f32_32x32x16_bf16 v[96:111], v[212:215], v[144:147], v[96:111]
	ds_read_b64_tr_b16 v[168:169], v242 offset:0x600
	ds_read_b64_tr_b16 v[170:171], v242 offset:0x700
	s_waitcnt lgkmcnt(10)
	v_mfma_f32_32x32x16_bf16 v[128:143], v[224:227], v[148:151], v[128:143]
	v_mfma_f32_32x32x16_bf16 v[96:111], v[220:223], v[148:151], v[96:111]
	ds_read_b64_tr_b16 v[172:173], v242 offset:0x1600
	ds_read_b64_tr_b16 v[174:175], v242 offset:0x1700
	s_waitcnt lgkmcnt(10)
	v_mfma_f32_32x32x16_bf16 v[112:127], v[216:219], v[152:155], v[112:127]
	v_mfma_f32_32x32x16_bf16 v[80:95], v[212:215], v[152:155], v[80:95]
	s_waitcnt lgkmcnt(8)
	v_mfma_f32_32x32x16_bf16 v[112:127], v[224:227], v[156:159], v[112:127]
	v_mfma_f32_32x32x16_bf16 v[80:95], v[220:223], v[156:159], v[80:95]
	ds_read_b128 v[144:147], v241 offset:0x2000
	ds_read_b128 v[148:151], v240 offset:0x2000
	ds_read_b128 v[152:155], v239 offset:0x2000
	ds_read_b128 v[156:159], v0 offset:0x2000
	s_waitcnt lgkmcnt(10)
	v_mfma_f32_32x32x16_bf16 v[64:79], v[216:219], v[160:163], v[64:79]
	v_mfma_f32_32x32x16_bf16 v[32:47], v[212:215], v[160:163], v[32:47]
	s_waitcnt lgkmcnt(8)
	v_mfma_f32_32x32x16_bf16 v[64:79], v[224:227], v[164:167], v[64:79]
	v_mfma_f32_32x32x16_bf16 v[32:47], v[220:223], v[164:167], v[32:47]
	s_waitcnt lgkmcnt(6)
	v_mfma_f32_32x32x16_bf16 v[48:63], v[216:219], v[168:171], v[48:63]
	v_mfma_f32_32x32x16_bf16 v[16:31], v[212:215], v[168:171], v[16:31]
	s_waitcnt lgkmcnt(4)
	v_mfma_f32_32x32x16_bf16 v[48:63], v[224:227], v[172:175], v[48:63]
	v_mfma_f32_32x32x16_bf16 v[16:31], v[220:223], v[172:175], v[16:31]
	s_waitcnt lgkmcnt(0)
	s_waitcnt lgkmcnt(0)
	v_mfma_f32_32x32x16_bf16 v[160:175], v[144:147], v[176:179], 0
	v_cmp_eq_f32_e32 vcc, 0, v238
	s_cmp_eq_u64 vcc, exec
	v_mfma_f32_32x32x16_bf16 v[160:175], v[148:151], v[180:183], v[160:175]
	v_mfma_f32_32x32x16_bf16 v[160:175], v[152:155], v[184:187], v[160:175]
	v_mfma_f32_32x32x16_bf16 v[160:175], v[156:159], v[188:191], v[160:175]
	s_cbranch_scc0 .LBB0_443

.LBB0_416:
	v_exp_f32_e32 v159, v175
	v_pk_add_f32 v[160:161], v[144:145], v[146:147]
	v_pk_add_f32 v[162:163], v[148:149], v[150:151]
	v_pk_add_f32 v[160:161], v[152:153], v[160:161]
	v_pk_add_f32 v[162:163], v[154:155], v[162:163]
	v_pk_add_f32 v[160:161], v[156:157], v[160:161]
	v_pk_add_f32 v[162:163], v[158:159], v[162:163]
	s_nop 0
	v_pk_add_f32 v[160:161], v[160:161], v[162:163]
	s_nop 0
	v_pk_add_f32 v[160:161], v[160:161], v[160:161] op_sel:[0,1] op_sel_hi:[1,0]
	s_nop 0
	v_cmp_lt_f32_e32 vcc, s58, v160
	v_cmp_gt_f32_e64 s[10:11], s59, v160
	s_and_b64 s[0:1], vcc, s[10:11]
	s_cmp_lg_u64 s[0:1], exec
	s_cselect_b64 vcc, -1, 0
	s_cbranch_vccnz .LBB0_418
	v_cvt_pk_bf16_f32 v6, v144, v145
	v_cvt_pk_bf16_f32 v7, v146, v147
	v_cvt_pk_bf16_f32 v8, v148, v149
	v_cvt_pk_bf16_f32 v9, v150, v151
	v_cvt_pk_bf16_f32 v208, v152, v153
	v_cvt_pk_bf16_f32 v209, v154, v155
	v_cvt_pk_bf16_f32 v210, v156, v157
	v_cvt_pk_bf16_f32 v211, v158, v159
	v_add_f32_e32 v15, v15, v160

.LBB0_422:
	v_exp_f32_e32 v159, v175
	v_pk_add_f32 v[160:161], v[144:145], v[146:147]
	v_pk_add_f32 v[162:163], v[148:149], v[150:151]
	v_pk_add_f32 v[160:161], v[152:153], v[160:161]
	v_pk_add_f32 v[162:163], v[154:155], v[162:163]
	v_pk_add_f32 v[160:161], v[156:157], v[160:161]
	v_pk_add_f32 v[162:163], v[158:159], v[162:163]
	s_nop 0
	v_pk_add_f32 v[160:161], v[160:161], v[162:163]
	s_nop 0
	v_pk_add_f32 v[160:161], v[160:161], v[160:161] op_sel:[0,1] op_sel_hi:[1,0]
	s_nop 0
	v_cmp_lt_f32_e32 vcc, s58, v160
	v_cmp_gt_f32_e64 s[10:11], s59, v160
	s_and_b64 s[0:1], vcc, s[10:11]
	s_cmp_lg_u64 s[0:1], exec
	s_cselect_b64 vcc, -1, 0
	s_cbranch_vccnz .LBB0_424
	v_cvt_pk_bf16_f32 v2, v144, v145
	v_cvt_pk_bf16_f32 v3, v146, v147
	v_cvt_pk_bf16_f32 v4, v148, v149
	v_cvt_pk_bf16_f32 v5, v150, v151
	v_cvt_pk_bf16_f32 v10, v152, v153
	v_cvt_pk_bf16_f32 v11, v154, v155
	v_cvt_pk_bf16_f32 v12, v156, v157
	v_cvt_pk_bf16_f32 v13, v158, v159
	v_add_f32_e32 v14, v14, v160

.LBB0_429:
	s_andn2_b64 vcc, exec, s[46:47]
	s_cbranch_vccnz .LBB0_388
	ds_read_b64_tr_b16 v[144:145], v242 offset:0x2000
	ds_read_b64_tr_b16 v[146:147], v242 offset:0x2100
	ds_read_b64_tr_b16 v[148:149], v242 offset:0x3000
	ds_read_b64_tr_b16 v[150:151], v242 offset:0x3100
	ds_read_b64_tr_b16 v[152:153], v242 offset:0x2200
	ds_read_b64_tr_b16 v[154:155], v242 offset:0x2300
	ds_read_b64_tr_b16 v[156:157], v242 offset:0x3200
	ds_read_b64_tr_b16 v[158:159], v242 offset:0x3300
	ds_read_b64_tr_b16 v[160:161], v242 offset:0x2400
	ds_read_b64_tr_b16 v[162:163], v242 offset:0x2500
	ds_read_b64_tr_b16 v[164:165], v242 offset:0x3400
	ds_read_b64_tr_b16 v[166:167], v242 offset:0x3500
	s_waitcnt lgkmcnt(10)
	s_nop 0
	v_mfma_f32_32x32x16_bf16 v[128:143], v[6:9], v[144:147], v[128:143]
	v_mfma_f32_32x32x16_bf16 v[96:111], v[2:5], v[144:147], v[96:111]
	ds_read_b64_tr_b16 v[168:169], v242 offset:0x2600
	ds_read_b64_tr_b16 v[170:171], v242 offset:0x2700
	s_waitcnt lgkmcnt(10)
	v_mfma_f32_32x32x16_bf16 v[128:143], v[208:211], v[148:151], v[128:143]
	v_mfma_f32_32x32x16_bf16 v[96:111], v[10:13], v[148:151], v[96:111]
	ds_read_b64_tr_b16 v[172:173], v242 offset:0x3600
	ds_read_b64_tr_b16 v[174:175], v242 offset:0x3700
	s_waitcnt lgkmcnt(10)
	v_mfma_f32_32x32x16_bf16 v[112:127], v[6:9], v[152:155], v[112:127]
	v_mfma_f32_32x32x16_bf16 v[80:95], v[2:5], v[152:155], v[80:95]
	s_waitcnt lgkmcnt(8)
	v_mfma_f32_32x32x16_bf16 v[112:127], v[208:211], v[156:159], v[112:127]
	v_mfma_f32_32x32x16_bf16 v[80:95], v[10:13], v[156:159], v[80:95]
	s_waitcnt lgkmcnt(6)
	v_mfma_f32_32x32x16_bf16 v[64:79], v[6:9], v[160:163], v[64:79]
	v_mfma_f32_32x32x16_bf16 v[32:47], v[2:5], v[160:163], v[32:47]
	s_waitcnt lgkmcnt(4)
	v_mfma_f32_32x32x16_bf16 v[64:79], v[208:211], v[164:167], v[64:79]
	v_mfma_f32_32x32x16_bf16 v[32:47], v[10:13], v[164:167], v[32:47]
	s_waitcnt lgkmcnt(2)
	v_mfma_f32_32x32x16_bf16 v[48:63], v[6:9], v[168:171], v[48:63]
	v_mfma_f32_32x32x16_bf16 v[16:31], v[2:5], v[168:171], v[16:31]
	s_waitcnt lgkmcnt(0)
	v_mfma_f32_32x32x16_bf16 v[48:63], v[208:211], v[172:175], v[48:63]
	v_mfma_f32_32x32x16_bf16 v[16:31], v[10:13], v[172:175], v[16:31]
	s_branch .LBB0_388

.LBB0_436:
	v_add_f32_e32 v160, 0, v144
	v_add_f32_e32 v160, v145, v160
	v_add_f32_e32 v160, v146, v160
	v_add_f32_e32 v160, v147, v160
	v_add_f32_e32 v160, v148, v160
	v_add_f32_e32 v160, v149, v160
	v_add_f32_e32 v160, v150, v160
	v_add_f32_e32 v160, v151, v160
	v_add_f32_e32 v160, v152, v160
	v_add_f32_e32 v160, v153, v160
	v_add_f32_e32 v160, v154, v160
	v_exp_f32_e32 v159, v159
	v_add_f32_e32 v160, v155, v160
	v_add_f32_e32 v160, v156, v160
	v_add_f32_e32 v160, v157, v160
	v_add_f32_e32 v160, v158, v160
	v_add_f32_e32 v160, v159, v160
	v_fmac_f32_e32 v160, v15, v242
	v_cvt_pk_bf16_f32 v216, v144, v145
	v_cvt_pk_bf16_f32 v217, v146, v147
	v_cvt_pk_bf16_f32 v218, v148, v149
	v_cvt_pk_bf16_f32 v219, v150, v151
	v_cvt_pk_bf16_f32 v224, v152, v153
	v_cvt_pk_bf16_f32 v225, v154, v155
	v_cvt_pk_bf16_f32 v226, v156, v157
	v_cvt_pk_bf16_f32 v227, v158, v159
	s_nop 0
	v_mov_b32_e32 v15, v160
	s_branch .LBB0_403

.LBB0_442:
	v_add_f32_e32 v160, 0, v144
	v_add_f32_e32 v160, v145, v160
	v_add_f32_e32 v160, v146, v160
	v_add_f32_e32 v160, v147, v160
	v_add_f32_e32 v160, v148, v160
	v_add_f32_e32 v160, v149, v160
	v_add_f32_e32 v160, v150, v160
	v_add_f32_e32 v160, v151, v160
	v_add_f32_e32 v160, v152, v160
	v_add_f32_e32 v160, v153, v160
	v_add_f32_e32 v160, v154, v160
	v_exp_f32_e32 v159, v159
	v_add_f32_e32 v160, v155, v160
	v_add_f32_e32 v160, v156, v160
	v_add_f32_e32 v160, v157, v160
	v_add_f32_e32 v160, v158, v160
	v_add_f32_e32 v160, v159, v160
	v_fmac_f32_e32 v160, v14, v243
	v_cvt_pk_bf16_f32 v212, v144, v145
	v_cvt_pk_bf16_f32 v213, v146, v147
	v_cvt_pk_bf16_f32 v214, v148, v149
	v_cvt_pk_bf16_f32 v215, v150, v151
	v_cvt_pk_bf16_f32 v220, v152, v153
	v_cvt_pk_bf16_f32 v221, v154, v155
	v_cvt_pk_bf16_f32 v222, v156, v157
	v_cvt_pk_bf16_f32 v223, v158, v159
	s_nop 0
	v_mov_b32_e32 v14, v160
	v_cmp_neq_f32_e32 vcc, 1.0, v242
	v_cmp_neq_f32_e64 s[10:11], 1.0, v243
	s_or_b64 vcc, vcc, s[10:11]
	s_cbranch_vccnz .LBB0_410
	s_branch .LBB0_413

.LBB0_448:
	v_exp_f32_e32 v159, v6
	v_add_f32_e32 v6, 0, v144
	v_add_f32_e32 v6, v145, v6
	v_add_f32_e32 v6, v146, v6
	v_add_f32_e32 v6, v147, v6
	v_add_f32_e32 v6, v148, v6
	v_add_f32_e32 v6, v149, v6
	v_add_f32_e32 v6, v150, v6
	v_add_f32_e32 v6, v151, v6
	v_add_f32_e32 v6, v152, v6
	v_add_f32_e32 v6, v153, v6
	v_add_f32_e32 v6, v154, v6
	v_add_f32_e32 v6, v155, v6
	v_add_f32_e32 v6, v156, v6
	v_add_f32_e32 v6, v157, v6
	v_add_f32_e32 v6, v158, v6
	v_add_f32_e32 v6, v159, v6
	v_mov_b32_e32 v160, v6
	v_fmac_f32_e32 v160, v15, v243
	v_cvt_pk_bf16_f32 v6, v144, v145
	v_cvt_pk_bf16_f32 v7, v146, v147
	v_cvt_pk_bf16_f32 v8, v148, v149
	v_cvt_pk_bf16_f32 v9, v150, v151
	v_cvt_pk_bf16_f32 v208, v152, v153
	v_cvt_pk_bf16_f32 v209, v154, v155
	v_cvt_pk_bf16_f32 v210, v156, v157
	v_cvt_pk_bf16_f32 v211, v158, v159
	s_nop 0
	v_mov_b32_e32 v15, v160
	s_branch .LBB0_419

.LBB0_454:
	v_add_f32_e32 v2, 0, v144
	v_add_f32_e32 v2, v145, v2
	v_add_f32_e32 v2, v146, v2
	v_add_f32_e32 v2, v147, v2
	v_add_f32_e32 v2, v148, v2
	v_add_f32_e32 v2, v149, v2
	v_add_f32_e32 v2, v150, v2
	v_add_f32_e32 v2, v151, v2
	v_add_f32_e32 v2, v152, v2
	v_add_f32_e32 v2, v153, v2
	v_add_f32_e32 v2, v154, v2
	v_exp_f32_e32 v0, v0
	v_add_f32_e32 v2, v155, v2
	v_add_f32_e32 v2, v156, v2
	v_add_f32_e32 v2, v157, v2
	v_add_f32_e32 v2, v158, v2
	v_add_f32_e32 v2, v0, v2
	v_mov_b32_e32 v159, v2
	v_fmac_f32_e32 v159, v14, v244
	v_cvt_pk_bf16_f32 v2, v144, v145
	v_cvt_pk_bf16_f32 v3, v146, v147
	v_cvt_pk_bf16_f32 v4, v148, v149
	v_cvt_pk_bf16_f32 v5, v150, v151
	v_cvt_pk_bf16_f32 v10, v152, v153
	v_cvt_pk_bf16_f32 v11, v154, v155
	v_cvt_pk_bf16_f32 v12, v156, v157
	v_cvt_pk_bf16_f32 v13, v158, v0
	s_nop 0
	v_mov_b32_e32 v14, v159
	v_cmp_neq_f32_e32 vcc, 1.0, v243
	v_cmp_neq_f32_e64 s[10:11], 1.0, v244
	s_or_b64 vcc, vcc, s[10:11]
	s_cbranch_vccnz .LBB0_426
	s_branch .LBB0_429

.LBB0_463:
	s_and_b64 vcc, exec, s[34:35]
	s_cbranch_vccz .LBB0_465
	s_cmp_lg_u32 0, -1
	s_cselect_b32 s0, 0, 0
	s_add_i32 s0, s0, 0xc000
	v_add_u32_e32 v0, s0, v232
	ds_read_b64_tr_b16 v[144:145], v0 offset:0x2000
	ds_read_b64_tr_b16 v[146:147], v0 offset:0x2100
	ds_read_b64_tr_b16 v[148:149], v0 offset:0x3000
	ds_read_b64_tr_b16 v[150:151], v0 offset:0x3100
	ds_read_b64_tr_b16 v[152:153], v0 offset:0x2200
	ds_read_b64_tr_b16 v[154:155], v0 offset:0x2300
	ds_read_b64_tr_b16 v[156:157], v0 offset:0x3200
	ds_read_b64_tr_b16 v[158:159], v0 offset:0x3300
	ds_read_b64_tr_b16 v[160:161], v0 offset:0x2400
	ds_read_b64_tr_b16 v[162:163], v0 offset:0x2500
	ds_read_b64_tr_b16 v[164:165], v0 offset:0x3400
	ds_read_b64_tr_b16 v[166:167], v0 offset:0x3500
	s_waitcnt lgkmcnt(10)
	s_nop 0
	v_mfma_f32_32x32x16_bf16 v[128:143], v[6:9], v[144:147], v[128:143]
	v_mfma_f32_32x32x16_bf16 v[96:111], v[2:5], v[144:147], v[96:111]
	ds_read_b64_tr_b16 v[168:169], v0 offset:0x2600
	ds_read_b64_tr_b16 v[170:171], v0 offset:0x2700
	s_waitcnt lgkmcnt(10)
	v_mfma_f32_32x32x16_bf16 v[128:143], v[208:211], v[148:151], v[128:143]
	v_mfma_f32_32x32x16_bf16 v[96:111], v[10:13], v[148:151], v[96:111]
	ds_read_b64_tr_b16 v[172:173], v0 offset:0x3600
	ds_read_b64_tr_b16 v[174:175], v0 offset:0x3700
	s_waitcnt lgkmcnt(10)
	v_mfma_f32_32x32x16_bf16 v[112:127], v[6:9], v[152:155], v[112:127]
	v_mfma_f32_32x32x16_bf16 v[80:95], v[2:5], v[152:155], v[80:95]
	s_waitcnt lgkmcnt(8)
	v_mfma_f32_32x32x16_bf16 v[112:127], v[208:211], v[156:159], v[112:127]
	v_mfma_f32_32x32x16_bf16 v[80:95], v[10:13], v[156:159], v[80:95]
	s_waitcnt lgkmcnt(6)
	v_mfma_f32_32x32x16_bf16 v[64:79], v[6:9], v[160:163], v[64:79]
	v_mfma_f32_32x32x16_bf16 v[32:47], v[2:5], v[160:163], v[32:47]
	s_waitcnt lgkmcnt(4)
	v_mfma_f32_32x32x16_bf16 v[64:79], v[208:211], v[164:167], v[64:79]
	v_mfma_f32_32x32x16_bf16 v[32:47], v[10:13], v[164:167], v[32:47]
	s_waitcnt lgkmcnt(2)
	v_mfma_f32_32x32x16_bf16 v[48:63], v[6:9], v[168:171], v[48:63]
	v_mfma_f32_32x32x16_bf16 v[16:31], v[2:5], v[168:171], v[16:31]
	s_waitcnt lgkmcnt(0)
	v_mfma_f32_32x32x16_bf16 v[48:63], v[208:211], v[172:175], v[48:63]
	v_mfma_f32_32x32x16_bf16 v[16:31], v[10:13], v[172:175], v[16:31]
.LBB0_465:
	v_mov_b32_e32 v252, v15
	v_mov_b32_e32 v253, v14
	s_nop 1
	v_permlane32_swap_b32_e32 v15, v252
	v_permlane32_swap_b32_e32 v14, v253
	v_add_f32_e32 v15, v15, v252
	v_add_f32_e32 v14, v14, v253
	v_mov_b32_e32 v2, v228
	v_readlane_b32 s50, v249, 48
	v_bfe_u32 v5, v2, 5, 1
	v_and_b32_e32 v3, 0x3fffffc0, v2
	v_readlane_b32 s44, v249, 57
	v_readlane_b32 s45, v249, 58
	v_and_b32_e32 v0, 31, v2
	v_lshl_add_u32 v3, v3, 2, s31
	v_cmp_eq_u32_e32 vcc, 0, v5
	v_readlane_b32 s51, v249, 49
	s_and_saveexec_b64 s[0:1], vcc
	s_cbranch_execz .LBB0_386
	v_div_scale_f32 v4, s[8:9], v15, v15, 1.0
	v_rcp_f32_e32 v6, v4
	v_div_scale_f32 v7, vcc, 1.0, v15, 1.0
	v_fma_f32 v8, -v4, v6, 1.0
	v_fmac_f32_e32 v6, v8, v6
	v_mul_f32_e32 v8, v7, v6
	v_fma_f32 v9, -v4, v8, v7
	v_fmac_f32_e32 v8, v9, v6
	v_fma_f32 v4, -v4, v8, v7
	v_div_scale_f32 v7, s[8:9], v14, v14, v229
	v_rcp_f32_e32 v9, v7
	v_div_fmas_f32 v4, v4, v6, v8
	v_div_fixup_f32 v4, v4, v15, 1.0
	v_lshl_add_u32 v6, v0, 2, v3
	v_fma_f32 v8, -v7, v9, 1.0
	v_fmac_f32_e32 v9, v8, v9
	v_div_scale_f32 v8, vcc, v229, v14, v229
	v_mul_f32_e32 v10, v8, v9
	v_fma_f32 v11, -v7, v10, v8
	v_fmac_f32_e32 v10, v11, v9
	v_fma_f32 v7, -v7, v10, v8
	v_div_fmas_f32 v7, v7, v9, v10
	v_div_fixup_f32 v7, v7, v14, v229
	ds_write2_b32 v6, v4, v7 offset1:32
	s_branch .LBB0_386

.LBB0_1241:
	s_ashr_i32 s0, s42, 31
	s_lshr_b32 s0, s0, 26
	s_add_i32 s0, s42, s0
	s_ashr_i32 s6, s0, 6
	s_and_b32 s0, s0, 0xffffc0
	s_sub_i32 s3, s42, s0
	s_ashr_i32 s7, s6, 31
	s_mul_i32 s11, s6, 0x17000000
	s_mul_hi_i32 s10, s6, 0x17000000
	s_add_u32 s0, s38, s11
	v_mov_b32_e32 v4, v228
	s_addc_u32 s1, s39, s10
	s_lshl_b32 s56, s3, 8
	v_mov_b64_e32 v[2:3], s[0:1]
	v_and_b32_e32 v6, 31, v4
	v_ashrrev_i32_e32 v5, 6, v4
	v_or_b32_e32 v0, s56, v6
	v_lshl_add_u32 v0, v5, 5, v0
	v_bfe_u32 v7, v4, 5, 1
	v_mad_i64_i32 v[2:3], s[8:9], v0, s30, v[2:3]
	v_lshl_add_u64 v[2:3], v[2:3], 0, s[12:13]
	v_lshlrev_b32_e32 v0, 4, v7
	v_lshl_add_u64 v[2:3], v[2:3], 0, v[0:1]
	v_readfirstlane_b32 s3, v5
	v_mov_b32_e32 v5, v228
	global_load_dwordx4 v[176:179], v[2:3], off
	global_load_dwordx4 v[180:183], v[2:3], off offset:32
	global_load_dwordx4 v[184:187], v[2:3], off offset:64
	global_load_dwordx4 v[188:191], v[2:3], off offset:96
	global_load_dwordx4 v[192:195], v[2:3], off offset:128
	global_load_dwordx4 v[196:199], v[2:3], off offset:160
	global_load_dwordx4 v[200:203], v[2:3], off offset:192
	global_load_dwordx4 v[204:207], v[2:3], off offset:224
	s_barrier
	s_add_u32 s0, s0, s12
	v_and_b32_e32 v3, 0x60, v5
	v_lshlrev_b32_e32 v9, 3, v5
	v_bfe_u32 v2, v5, 2, 2
	v_and_or_b32 v9, v9, 24, v3
	v_lshrrev_b32_e32 v3, 1, v5
	v_and_b32_e32 v8, 15, v5
	v_and_or_b32 v10, v3, 8, v2
	v_ashrrev_i32_e32 v3, 4, v5
	v_bitop3_b32 v2, v3, v8, 7 bitop3:0x6c
	v_mul_lo_u32 v11, v3, s30
	v_lshl_or_b32 v2, v2, 4, v11
	v_and_b32_e32 v11, 0x7ffff0, v3
	v_lshrrev_b32_e32 v3, 1, v3
	v_and_b32_e32 v3, 4, v3
	s_addc_u32 s1, s1, s13
	v_or3_b32 v3, v11, v3, v10
	s_add_u32 s8, s0, 0x1000
	v_mul_u32_u24_e32 v3, 0x2e00, v3
	s_addc_u32 s9, s1, 0
	s_lshl_b32 s24, s3, 10
	v_or_b32_e32 v3, v3, v9
	s_add_i32 s57, s24, 0
	v_lshlrev_b32_e32 v11, 1, v3
	v_mov_b32_e32 v3, v1
	s_add_i32 s68, s57, 0x10000
	v_lshl_add_u64 v[2:3], s[0:1], 0, v[2:3]
	v_lshl_add_u64 v[2:3], v[2:3], 0, s[14:15]
	s_mov_b32 m0, s68
	v_mov_b32_e32 v14, v1
	global_load_lds_dwordx4 v[2:3], off
	v_add_u32_e32 v2, 0x200, v5
	v_ashrrev_i32_e32 v3, 4, v2
	v_bitop3_b32 v2, v3, v8, 7 bitop3:0x6c
	v_mul_lo_u32 v5, v3, s30
	v_lshl_or_b32 v2, v2, 4, v5
	v_and_b32_e32 v5, 0x7ffff0, v3
	v_lshrrev_b32_e32 v3, 1, v3
	v_and_b32_e32 v3, 4, v3
	v_or3_b32 v3, v5, v3, v10
	v_mul_u32_u24_e32 v3, 0x2e00, v3
	v_or_b32_e32 v3, v3, v9
	v_lshlrev_b32_e32 v5, 1, v3
	v_mov_b32_e32 v3, v1
	s_mov_b32 m0, s57
	v_lshl_add_u64 v[2:3], s[0:1], 0, v[2:3]
	global_load_lds_dwordx4 v11, s[8:9]
	v_lshl_add_u64 v[2:3], v[2:3], 0, s[14:15]
	s_add_i32 m0, s57, 0x12000
	v_mov_b32_e32 v15, v1
	global_load_lds_dwordx4 v[2:3], off
	s_add_i32 m0, s57, 0x2000
	v_mov_b32_e32 v2, v228
	global_load_lds_dwordx4 v5, s[8:9]
	s_cmp_lg_u32 0, -1
	v_and_b32_e32 v8, 0x60, v2
	v_lshlrev_b32_e32 v9, 3, v2
	v_bfe_u32 v5, v2, 2, 2
	v_and_or_b32 v8, v9, 24, v8
	v_lshrrev_b32_e32 v9, 1, v2
	v_and_b32_e32 v3, 15, v2
	v_and_or_b32 v5, v9, 8, v5
	v_ashrrev_i32_e32 v9, 4, v2
	s_cselect_b32 s24, 0, 0
	v_bitop3_b32 v10, v9, v3, 7 bitop3:0x6c
	v_mul_lo_u32 v11, v9, s30
	s_add_i32 s27, s24, 0x10000
	v_lshl_or_b32 v10, v10, 4, v11
	v_and_b32_e32 v11, 0x7ffff0, v9
	v_lshrrev_b32_e32 v9, 1, v9
	s_add_u32 s8, s0, 0x170800
	v_and_b32_e32 v9, 4, v9
	s_addc_u32 s9, s1, 0
	v_or3_b32 v9, v11, v9, v5
	s_add_u32 s0, s0, 0x171000
	v_mul_u32_u24_e32 v9, 0x2e00, v9
	s_addc_u32 s1, s1, 0
	s_add_i32 m0, s57, 0x14000
	s_add_i32 s33, s57, 0x4000
	v_or_b32_e32 v9, v9, v8
	v_add_u32_e32 v2, 0x200, v2
	v_lshlrev_b32_e32 v9, 1, v9
	global_load_lds_dwordx4 v10, s[8:9]
	s_mov_b32 m0, s33
	v_ashrrev_i32_e32 v2, 4, v2
	global_load_lds_dwordx4 v9, s[0:1]
	v_bitop3_b32 v3, v2, v3, 7 bitop3:0x6c
	v_mul_lo_u32 v9, v2, s30
	v_lshl_or_b32 v3, v3, 4, v9
	v_and_b32_e32 v9, 0x7ffff0, v2
	v_lshrrev_b32_e32 v2, 1, v2
	v_and_b32_e32 v2, 4, v2
	v_or3_b32 v2, v9, v2, v5
	v_mul_u32_u24_e32 v2, 0x2e00, v2
	v_or_b32_e32 v2, v2, v8
	s_add_i32 m0, s57, 0x16000
	v_lshlrev_b32_e32 v2, 1, v2
	global_load_lds_dwordx4 v3, s[8:9]
	s_add_i32 m0, s57, 0x6000
	v_and_b32_e32 v3, 63, v4
	global_load_lds_dwordx4 v2, s[0:1]
	v_lshlrev_b32_e32 v8, 4, v4
	v_lshlrev_b32_e32 v5, 3, v3
	v_and_b32_e32 v8, 0xc0, v8
	v_lshlrev_b32_e32 v9, 1, v4
	v_and_b32_e32 v2, 0x3fffffc0, v4
	v_and_or_b32 v8, v5, 24, v8
	v_and_b32_e32 v9, 32, v9
	v_and_b32_e32 v5, 0x100, v5
	v_lshlrev_b32_e32 v5, 3, v5
	v_bitop3_b32 v4, v7, v4, 7 bitop3:0x78
	s_cmp_gt_i32 s3, 3
	v_lshl_add_u32 v2, v2, 2, s25
	v_or3_b32 v232, v8, v9, v5
	v_lshlrev_b32_e32 v5, 8, v6
	v_lshlrev_b32_e32 v4, 4, v4
	s_cselect_b64 s[34:35], -1, 0
	s_cmp_lt_i32 s3, 4
	v_add3_u32 v233, v5, s27, v4
	s_cselect_b64 s[84:85], -1, 0
	v_cmp_gt_u32_e64 s[8:9], 32, v3
	v_lshl_add_u32 v235, v6, 2, v2
	v_add_u32_e32 v236, v2, v0
	s_add_u32 s69, s18, s11
	v_mov_b32_e32 v0, v1
	v_mov_b32_e32 v2, v1
	v_mov_b32_e32 v3, v1
	v_mov_b32_e32 v4, v1
	v_mov_b32_e32 v5, v1
	v_mov_b32_e32 v6, v1
	v_mov_b32_e32 v7, v1
	v_mov_b32_e32 v8, v1
	v_mov_b32_e32 v9, v1
	v_mov_b32_e32 v10, v1
	v_mov_b32_e32 v11, v1
	v_mov_b32_e32 v12, v1
	v_mov_b32_e32 v13, v1
	v_mov_b64_e32 v[110:111], v[14:15]
	v_mov_b64_e32 v[94:95], v[14:15]
	v_mov_b64_e32 v[62:63], v[14:15]
	v_mov_b64_e32 v[30:31], v[14:15]
	v_mov_b64_e32 v[142:143], v[14:15]
	v_mov_b64_e32 v[126:127], v[14:15]
	v_mov_b64_e32 v[78:79], v[14:15]
	v_mov_b64_e32 v[46:47], v[14:15]
	v_add_u32_e32 v234, s24, v232
	s_addc_u32 s76, s19, s10
	s_mov_b64 s[86:87], 0
	s_xor_b64 s[88:89], s[34:35], -1
	s_mov_b32 s77, 0
	v_mov_b64_e32 v[108:109], v[12:13]
	v_mov_b64_e32 v[106:107], v[10:11]
	v_mov_b64_e32 v[104:105], v[8:9]
	v_mov_b64_e32 v[102:103], v[6:7]
	v_mov_b64_e32 v[100:101], v[4:5]
	v_mov_b64_e32 v[98:99], v[2:3]
	v_mov_b64_e32 v[96:97], v[0:1]
	v_mov_b64_e32 v[92:93], v[12:13]
	v_mov_b64_e32 v[90:91], v[10:11]
	v_mov_b64_e32 v[88:89], v[8:9]
	v_mov_b64_e32 v[86:87], v[6:7]
	v_mov_b64_e32 v[84:85], v[4:5]
	v_mov_b64_e32 v[82:83], v[2:3]
	v_mov_b64_e32 v[80:81], v[0:1]
	v_mov_b64_e32 v[60:61], v[12:13]
	v_mov_b64_e32 v[58:59], v[10:11]
	v_mov_b64_e32 v[56:57], v[8:9]
	v_mov_b64_e32 v[54:55], v[6:7]
	v_mov_b64_e32 v[52:53], v[4:5]
	v_mov_b64_e32 v[50:51], v[2:3]
	v_mov_b64_e32 v[48:49], v[0:1]
	v_mov_b64_e32 v[28:29], v[12:13]
	v_mov_b64_e32 v[26:27], v[10:11]
	v_mov_b64_e32 v[24:25], v[8:9]
	v_mov_b64_e32 v[22:23], v[6:7]
	v_mov_b64_e32 v[20:21], v[4:5]
	v_mov_b64_e32 v[18:19], v[2:3]
	v_mov_b64_e32 v[16:17], v[0:1]
	v_mov_b64_e32 v[140:141], v[12:13]
	v_mov_b64_e32 v[138:139], v[10:11]
	v_mov_b64_e32 v[136:137], v[8:9]
	v_mov_b64_e32 v[134:135], v[6:7]
	v_mov_b64_e32 v[132:133], v[4:5]
	v_mov_b64_e32 v[130:131], v[2:3]
	v_mov_b64_e32 v[128:129], v[0:1]
	v_mov_b64_e32 v[124:125], v[12:13]
	v_mov_b64_e32 v[122:123], v[10:11]
	v_mov_b64_e32 v[120:121], v[8:9]
	v_mov_b64_e32 v[118:119], v[6:7]
	v_mov_b64_e32 v[116:117], v[4:5]
	v_mov_b64_e32 v[114:115], v[2:3]
	v_mov_b64_e32 v[112:113], v[0:1]
	v_mov_b64_e32 v[76:77], v[12:13]
	v_mov_b64_e32 v[74:75], v[10:11]
	v_mov_b64_e32 v[72:73], v[8:9]
	v_mov_b64_e32 v[70:71], v[6:7]
	v_mov_b64_e32 v[68:69], v[4:5]
	v_mov_b64_e32 v[66:67], v[2:3]
	v_mov_b64_e32 v[64:65], v[0:1]
	v_mov_b64_e32 v[44:45], v[12:13]
	v_mov_b64_e32 v[42:43], v[10:11]
	v_mov_b64_e32 v[40:41], v[8:9]
	v_mov_b64_e32 v[38:39], v[6:7]
	v_mov_b64_e32 v[36:37], v[4:5]
	v_mov_b64_e32 v[34:35], v[2:3]
	v_mov_b64_e32 v[32:33], v[0:1]
	s_mov_b32 s79, 0
	v_mov_b32_e32 v237, v1
	v_mov_b32_e32 v238, v1
	v_mov_b32_e32 v208, v1
	v_mov_b32_e32 v209, v1
	v_mov_b32_e32 v210, v1
	v_mov_b32_e32 v211, v1
	v_lshrrev_b32_e32 v250, 4, v228
	v_and_b32_e32 v251, 15, v228
	v_and_b32_e32 v252, 7, v250
	v_xor_b32_e32 v251, v251, v252
	v_mul_u32_u24_e32 v250, 0x5c00, v250
	v_lshl_or_b32 v250, v251, 4, v250
	v_bfe_u32 v251, v228, 2, 2
	v_bfe_u32 v252, v228, 7, 1
	v_lshl_or_b32 v251, v252, 2, v251
	v_bfe_u32 v252, v228, 4, 1
	v_lshl_or_b32 v251, v252, 3, v251
	v_bfe_u32 v252, v228, 8, 1
	v_lshl_or_b32 v251, v252, 4, v251
	v_mul_u32_u24_e32 v251, 0x5c00, v251
	v_bfe_u32 v252, v228, 5, 2
	v_lshl_or_b32 v251, v252, 6, v251
	v_and_b32_e32 v252, 3, v228
	v_lshl_or_b32 v251, v252, 4, v251
	s_waitcnt vmcnt(0)
	s_branch .LBB0_1243

.LBB0_1247:
	s_barrier
	s_cmpk_gt_u32 s79, 0xfd
	s_cbranch_scc1 .LBB0_1249
	s_add_i32 s3, s77, 0x8000
	s_and_b32 s3, s3, 0xc000
	s_add_u32 s0, s69, s86
	s_addc_u32 s1, s76, s87
	s_add_u32 s10, s0, s36
	s_addc_u32 s11, s1, s37
	s_add_u32 s0, s0, s16
	s_addc_u32 s1, s1, s17
	s_add_i32 m0, s68, s3
	s_nop 0
	global_load_lds_dwordx4 v250, s[0:1]
	s_add_i32 m0, s57, s3
	s_add_i32 s3, s3, 0x2000
	global_load_lds_dwordx4 v251, s[10:11]
	s_add_u32 s0, s0, 0xb8000
	s_addc_u32 s1, s1, 0
	s_add_i32 m0, s68, s3
	s_add_u32 s10, s10, 0xb8000
	s_addc_u32 s11, s11, 0
	global_load_lds_dwordx4 v250, s[0:1]
	s_add_i32 m0, s57, s3
	s_nop 0
	global_load_lds_dwordx4 v251, s[10:11]
.LBB0_1249:
	s_cmp_eq_u32 s86, 0
	s_cselect_b64 s[0:1], -1, 0
	s_or_b64 s[0:1], s[88:89], s[0:1]
	s_and_b64 vcc, exec, s[0:1]
	s_cbranch_vccnz .LBB0_1251
	s_add_i32 s0, s77, 0xc000
	s_and_b32 s0, s0, 0xc000
	v_add_u32_e32 v0, s0, v234
	ds_read_b64_tr_b16 v[144:145], v0 offset:0x2000
	ds_read_b64_tr_b16 v[146:147], v0 offset:0x2100
	ds_read_b64_tr_b16 v[148:149], v0 offset:0x3000
	ds_read_b64_tr_b16 v[150:151], v0 offset:0x3100
	ds_read_b64_tr_b16 v[152:153], v0 offset:0x2200
	ds_read_b64_tr_b16 v[154:155], v0 offset:0x2300
	ds_read_b64_tr_b16 v[156:157], v0 offset:0x3200
	ds_read_b64_tr_b16 v[158:159], v0 offset:0x3300
	ds_read_b64_tr_b16 v[160:161], v0 offset:0x2400
	ds_read_b64_tr_b16 v[162:163], v0 offset:0x2500
	ds_read_b64_tr_b16 v[164:165], v0 offset:0x3400
	ds_read_b64_tr_b16 v[166:167], v0 offset:0x3500
	s_waitcnt lgkmcnt(10)
	s_nop 0
	v_mfma_f32_32x32x16_bf16 v[128:143], v[6:9], v[144:147], v[128:143]
	v_mfma_f32_32x32x16_bf16 v[96:111], v[2:5], v[144:147], v[96:111]
	ds_read_b64_tr_b16 v[168:169], v0 offset:0x2600
	ds_read_b64_tr_b16 v[170:171], v0 offset:0x2700
	s_waitcnt lgkmcnt(10)
	v_mfma_f32_32x32x16_bf16 v[128:143], v[208:211], v[148:151], v[128:143]
	v_mfma_f32_32x32x16_bf16 v[96:111], v[10:13], v[148:151], v[96:111]
	ds_read_b64_tr_b16 v[172:173], v0 offset:0x3600
	ds_read_b64_tr_b16 v[174:175], v0 offset:0x3700
	s_waitcnt lgkmcnt(10)
	v_mfma_f32_32x32x16_bf16 v[112:127], v[6:9], v[152:155], v[112:127]
	v_mfma_f32_32x32x16_bf16 v[80:95], v[2:5], v[152:155], v[80:95]
	s_waitcnt lgkmcnt(8)
	v_mfma_f32_32x32x16_bf16 v[112:127], v[208:211], v[156:159], v[112:127]
	v_mfma_f32_32x32x16_bf16 v[80:95], v[10:13], v[156:159], v[80:95]
	s_waitcnt lgkmcnt(6)
	v_mfma_f32_32x32x16_bf16 v[64:79], v[6:9], v[160:163], v[64:79]
	v_mfma_f32_32x32x16_bf16 v[48:63], v[2:5], v[160:163], v[48:63]
	s_waitcnt lgkmcnt(4)
	v_mfma_f32_32x32x16_bf16 v[64:79], v[208:211], v[164:167], v[64:79]
	v_mfma_f32_32x32x16_bf16 v[48:63], v[10:13], v[164:167], v[48:63]
	s_waitcnt lgkmcnt(2)
	v_mfma_f32_32x32x16_bf16 v[32:47], v[6:9], v[168:171], v[32:47]
	v_mfma_f32_32x32x16_bf16 v[16:31], v[2:5], v[168:171], v[16:31]
	s_waitcnt lgkmcnt(0)
	v_mfma_f32_32x32x16_bf16 v[32:47], v[208:211], v[172:175], v[32:47]
	v_mfma_f32_32x32x16_bf16 v[16:31], v[10:13], v[172:175], v[16:31]

.LBB0_1254:
	v_exp_f32_e32 v159, v175
	v_pk_add_f32 v[160:161], v[144:145], v[146:147]
	v_pk_add_f32 v[162:163], v[148:149], v[150:151]
	v_pk_add_f32 v[160:161], v[152:153], v[160:161]
	v_pk_add_f32 v[162:163], v[154:155], v[162:163]
	v_pk_add_f32 v[160:161], v[156:157], v[160:161]
	v_pk_add_f32 v[162:163], v[158:159], v[162:163]
	s_nop 0
	v_pk_add_f32 v[160:161], v[160:161], v[162:163]
	s_nop 0
	v_pk_add_f32 v[160:161], v[160:161], v[160:161] op_sel:[0,1] op_sel_hi:[1,0]
	s_nop 0
	v_cmp_lt_f32_e32 vcc, s52, v160
	v_cmp_gt_f32_e64 s[10:11], s53, v160
	s_and_b64 s[0:1], vcc, s[10:11]
	s_cmp_lg_u64 s[0:1], exec
	s_cselect_b64 vcc, -1, 0
	s_cbranch_vccnz .LBB0_1256
	v_cvt_pk_bf16_f32 v216, v144, v145
	v_cvt_pk_bf16_f32 v217, v146, v147
	v_cvt_pk_bf16_f32 v218, v148, v149
	v_cvt_pk_bf16_f32 v219, v150, v151
	v_cvt_pk_bf16_f32 v224, v152, v153
	v_cvt_pk_bf16_f32 v225, v154, v155
	v_cvt_pk_bf16_f32 v226, v156, v157
	v_cvt_pk_bf16_f32 v227, v158, v159
	v_add_f32_e32 v15, v15, v160

.LBB0_1260:
	v_exp_f32_e32 v159, v175
	v_pk_add_f32 v[160:161], v[144:145], v[146:147]
	v_pk_add_f32 v[162:163], v[148:149], v[150:151]
	v_pk_add_f32 v[160:161], v[152:153], v[160:161]
	v_pk_add_f32 v[162:163], v[154:155], v[162:163]
	v_pk_add_f32 v[160:161], v[156:157], v[160:161]
	v_pk_add_f32 v[162:163], v[158:159], v[162:163]
	s_nop 0
	v_pk_add_f32 v[160:161], v[160:161], v[162:163]
	s_nop 0
	v_pk_add_f32 v[160:161], v[160:161], v[160:161] op_sel:[0,1] op_sel_hi:[1,0]
	s_nop 0
	v_cmp_lt_f32_e32 vcc, s52, v160
	v_cmp_gt_f32_e64 s[10:11], s53, v160
	s_and_b64 s[0:1], vcc, s[10:11]
	s_cmp_lg_u64 s[0:1], exec
	s_cselect_b64 vcc, -1, 0
	s_cbranch_vccnz .LBB0_1262
	v_cvt_pk_bf16_f32 v212, v144, v145
	v_cvt_pk_bf16_f32 v213, v146, v147
	v_cvt_pk_bf16_f32 v214, v148, v149
	v_cvt_pk_bf16_f32 v215, v150, v151
	v_cvt_pk_bf16_f32 v220, v152, v153
	v_cvt_pk_bf16_f32 v221, v154, v155
	v_cvt_pk_bf16_f32 v222, v156, v157
	v_cvt_pk_bf16_f32 v223, v158, v159
	v_add_f32_e32 v14, v14, v160

.LBB0_1267:
	v_add_u32_e32 v242, s27, v234
	ds_read_b64_tr_b16 v[144:145], v242 offset:0x0
	ds_read_b64_tr_b16 v[146:147], v242 offset:0x100
	ds_read_b64_tr_b16 v[148:149], v242 offset:0x1000
	ds_read_b64_tr_b16 v[150:151], v242 offset:0x1100
	ds_read_b64_tr_b16 v[152:153], v242 offset:0x200
	ds_read_b64_tr_b16 v[154:155], v242 offset:0x300
	ds_read_b64_tr_b16 v[156:157], v242 offset:0x1200
	ds_read_b64_tr_b16 v[158:159], v242 offset:0x1300
	ds_read_b64_tr_b16 v[160:161], v242 offset:0x400
	ds_read_b64_tr_b16 v[162:163], v242 offset:0x500
	ds_read_b64_tr_b16 v[164:165], v242 offset:0x1400
	ds_read_b64_tr_b16 v[166:167], v242 offset:0x1500
	s_waitcnt lgkmcnt(10)
	s_nop 0
	v_mfma_f32_32x32x16_bf16 v[128:143], v[216:219], v[144:147], v[128:143]
	v_mfma_f32_32x32x16_bf16 v[96:111], v[212:215], v[144:147], v[96:111]
	ds_read_b64_tr_b16 v[168:169], v242 offset:0x600
	ds_read_b64_tr_b16 v[170:171], v242 offset:0x700
	s_waitcnt lgkmcnt(10)
	v_mfma_f32_32x32x16_bf16 v[128:143], v[224:227], v[148:151], v[128:143]
	v_mfma_f32_32x32x16_bf16 v[96:111], v[220:223], v[148:151], v[96:111]
	ds_read_b64_tr_b16 v[172:173], v242 offset:0x1600
	ds_read_b64_tr_b16 v[174:175], v242 offset:0x1700
	s_waitcnt lgkmcnt(10)
	v_mfma_f32_32x32x16_bf16 v[112:127], v[216:219], v[152:155], v[112:127]
	v_mfma_f32_32x32x16_bf16 v[80:95], v[212:215], v[152:155], v[80:95]
	s_waitcnt lgkmcnt(8)
	v_mfma_f32_32x32x16_bf16 v[112:127], v[224:227], v[156:159], v[112:127]
	v_mfma_f32_32x32x16_bf16 v[80:95], v[220:223], v[156:159], v[80:95]
	ds_read_b128 v[144:147], v241 offset:0x2000
	ds_read_b128 v[148:151], v240 offset:0x2000
	ds_read_b128 v[152:155], v239 offset:0x2000
	ds_read_b128 v[156:159], v0 offset:0x2000
	s_waitcnt lgkmcnt(10)
	v_mfma_f32_32x32x16_bf16 v[64:79], v[216:219], v[160:163], v[64:79]
	v_mfma_f32_32x32x16_bf16 v[48:63], v[212:215], v[160:163], v[48:63]
	s_waitcnt lgkmcnt(8)
	v_mfma_f32_32x32x16_bf16 v[64:79], v[224:227], v[164:167], v[64:79]
	v_mfma_f32_32x32x16_bf16 v[48:63], v[220:223], v[164:167], v[48:63]
	s_waitcnt lgkmcnt(6)
	v_mfma_f32_32x32x16_bf16 v[32:47], v[216:219], v[168:171], v[32:47]
	v_mfma_f32_32x32x16_bf16 v[16:31], v[212:215], v[168:171], v[16:31]
	s_waitcnt lgkmcnt(4)
	v_mfma_f32_32x32x16_bf16 v[32:47], v[224:227], v[172:175], v[32:47]
	v_mfma_f32_32x32x16_bf16 v[16:31], v[220:223], v[172:175], v[16:31]
	s_waitcnt lgkmcnt(0)
	s_waitcnt lgkmcnt(0)
	v_mfma_f32_32x32x16_bf16 v[160:175], v[144:147], v[176:179], 0
	v_cmp_eq_f32_e32 vcc, 0, v238
	s_cmp_eq_u64 vcc, exec
	v_mfma_f32_32x32x16_bf16 v[160:175], v[148:151], v[180:183], v[160:175]
	v_mfma_f32_32x32x16_bf16 v[160:175], v[152:155], v[184:187], v[160:175]
	v_mfma_f32_32x32x16_bf16 v[160:175], v[156:159], v[188:191], v[160:175]
	s_cbranch_scc0 .LBB0_1297

.LBB0_1270:
	v_exp_f32_e32 v159, v175
	v_pk_add_f32 v[160:161], v[144:145], v[146:147]
	v_pk_add_f32 v[162:163], v[148:149], v[150:151]
	v_pk_add_f32 v[160:161], v[152:153], v[160:161]
	v_pk_add_f32 v[162:163], v[154:155], v[162:163]
	v_pk_add_f32 v[160:161], v[156:157], v[160:161]
	v_pk_add_f32 v[162:163], v[158:159], v[162:163]
	s_nop 0
	v_pk_add_f32 v[160:161], v[160:161], v[162:163]
	s_nop 0
	v_pk_add_f32 v[160:161], v[160:161], v[160:161] op_sel:[0,1] op_sel_hi:[1,0]
	s_nop 0
	v_cmp_lt_f32_e32 vcc, s52, v160
	v_cmp_gt_f32_e64 s[10:11], s53, v160
	s_and_b64 s[0:1], vcc, s[10:11]
	s_cmp_lg_u64 s[0:1], exec
	s_cselect_b64 vcc, -1, 0
	s_cbranch_vccnz .LBB0_1272
	v_cvt_pk_bf16_f32 v6, v144, v145
	v_cvt_pk_bf16_f32 v7, v146, v147
	v_cvt_pk_bf16_f32 v8, v148, v149
	v_cvt_pk_bf16_f32 v9, v150, v151
	v_cvt_pk_bf16_f32 v208, v152, v153
	v_cvt_pk_bf16_f32 v209, v154, v155
	v_cvt_pk_bf16_f32 v210, v156, v157
	v_cvt_pk_bf16_f32 v211, v158, v159
	v_add_f32_e32 v15, v15, v160

.LBB0_1276:
	v_exp_f32_e32 v159, v175
	v_pk_add_f32 v[160:161], v[144:145], v[146:147]
	v_pk_add_f32 v[162:163], v[148:149], v[150:151]
	v_pk_add_f32 v[160:161], v[152:153], v[160:161]
	v_pk_add_f32 v[162:163], v[154:155], v[162:163]
	v_pk_add_f32 v[160:161], v[156:157], v[160:161]
	v_pk_add_f32 v[162:163], v[158:159], v[162:163]
	s_nop 0
	v_pk_add_f32 v[160:161], v[160:161], v[162:163]
	s_nop 0
	v_pk_add_f32 v[160:161], v[160:161], v[160:161] op_sel:[0,1] op_sel_hi:[1,0]
	s_nop 0
	v_cmp_lt_f32_e32 vcc, s52, v160
	v_cmp_gt_f32_e64 s[10:11], s53, v160
	s_and_b64 s[0:1], vcc, s[10:11]
	s_cmp_lg_u64 s[0:1], exec
	s_cselect_b64 vcc, -1, 0
	s_cbranch_vccnz .LBB0_1278
	v_cvt_pk_bf16_f32 v2, v144, v145
	v_cvt_pk_bf16_f32 v3, v146, v147
	v_cvt_pk_bf16_f32 v4, v148, v149
	v_cvt_pk_bf16_f32 v5, v150, v151
	v_cvt_pk_bf16_f32 v10, v152, v153
	v_cvt_pk_bf16_f32 v11, v154, v155
	v_cvt_pk_bf16_f32 v12, v156, v157
	v_cvt_pk_bf16_f32 v13, v158, v159
	v_add_f32_e32 v14, v14, v160

.LBB0_1283:
	s_andn2_b64 vcc, exec, s[84:85]
	s_cbranch_vccnz .LBB0_1242
	ds_read_b64_tr_b16 v[144:145], v242 offset:0x2000
	ds_read_b64_tr_b16 v[146:147], v242 offset:0x2100
	ds_read_b64_tr_b16 v[148:149], v242 offset:0x3000
	ds_read_b64_tr_b16 v[150:151], v242 offset:0x3100
	ds_read_b64_tr_b16 v[152:153], v242 offset:0x2200
	ds_read_b64_tr_b16 v[154:155], v242 offset:0x2300
	ds_read_b64_tr_b16 v[156:157], v242 offset:0x3200
	ds_read_b64_tr_b16 v[158:159], v242 offset:0x3300
	ds_read_b64_tr_b16 v[160:161], v242 offset:0x2400
	ds_read_b64_tr_b16 v[162:163], v242 offset:0x2500
	ds_read_b64_tr_b16 v[164:165], v242 offset:0x3400
	ds_read_b64_tr_b16 v[166:167], v242 offset:0x3500
	s_waitcnt lgkmcnt(10)
	s_nop 0
	v_mfma_f32_32x32x16_bf16 v[128:143], v[6:9], v[144:147], v[128:143]
	v_mfma_f32_32x32x16_bf16 v[96:111], v[2:5], v[144:147], v[96:111]
	ds_read_b64_tr_b16 v[168:169], v242 offset:0x2600
	ds_read_b64_tr_b16 v[170:171], v242 offset:0x2700
	s_waitcnt lgkmcnt(10)
	v_mfma_f32_32x32x16_bf16 v[128:143], v[208:211], v[148:151], v[128:143]
	v_mfma_f32_32x32x16_bf16 v[96:111], v[10:13], v[148:151], v[96:111]
	ds_read_b64_tr_b16 v[172:173], v242 offset:0x3600
	ds_read_b64_tr_b16 v[174:175], v242 offset:0x3700
	s_waitcnt lgkmcnt(10)
	v_mfma_f32_32x32x16_bf16 v[112:127], v[6:9], v[152:155], v[112:127]
	v_mfma_f32_32x32x16_bf16 v[80:95], v[2:5], v[152:155], v[80:95]
	s_waitcnt lgkmcnt(8)
	v_mfma_f32_32x32x16_bf16 v[112:127], v[208:211], v[156:159], v[112:127]
	v_mfma_f32_32x32x16_bf16 v[80:95], v[10:13], v[156:159], v[80:95]
	s_waitcnt lgkmcnt(6)
	v_mfma_f32_32x32x16_bf16 v[64:79], v[6:9], v[160:163], v[64:79]
	v_mfma_f32_32x32x16_bf16 v[48:63], v[2:5], v[160:163], v[48:63]
	s_waitcnt lgkmcnt(4)
	v_mfma_f32_32x32x16_bf16 v[64:79], v[208:211], v[164:167], v[64:79]
	v_mfma_f32_32x32x16_bf16 v[48:63], v[10:13], v[164:167], v[48:63]
	s_waitcnt lgkmcnt(2)
	v_mfma_f32_32x32x16_bf16 v[32:47], v[6:9], v[168:171], v[32:47]
	v_mfma_f32_32x32x16_bf16 v[16:31], v[2:5], v[168:171], v[16:31]
	s_waitcnt lgkmcnt(0)
	v_mfma_f32_32x32x16_bf16 v[32:47], v[208:211], v[172:175], v[32:47]
	v_mfma_f32_32x32x16_bf16 v[16:31], v[10:13], v[172:175], v[16:31]
	s_branch .LBB0_1242

.LBB0_1317:
	s_and_b64 vcc, exec, s[34:35]
	s_cbranch_vccz .LBB0_1319
	s_cmp_lg_u32 0, -1
	s_cselect_b32 s0, 0, 0
	s_add_i32 s0, s0, 0xc000
	v_add_u32_e32 v0, s0, v232
	ds_read_b64_tr_b16 v[144:145], v0 offset:0x2000
	ds_read_b64_tr_b16 v[146:147], v0 offset:0x2100
	ds_read_b64_tr_b16 v[148:149], v0 offset:0x3000
	ds_read_b64_tr_b16 v[150:151], v0 offset:0x3100
	ds_read_b64_tr_b16 v[152:153], v0 offset:0x2200
	ds_read_b64_tr_b16 v[154:155], v0 offset:0x2300
	ds_read_b64_tr_b16 v[156:157], v0 offset:0x3200
	ds_read_b64_tr_b16 v[158:159], v0 offset:0x3300
	ds_read_b64_tr_b16 v[160:161], v0 offset:0x2400
	ds_read_b64_tr_b16 v[162:163], v0 offset:0x2500
	ds_read_b64_tr_b16 v[164:165], v0 offset:0x3400
	ds_read_b64_tr_b16 v[166:167], v0 offset:0x3500
	s_waitcnt lgkmcnt(10)
	s_nop 0
	v_mfma_f32_32x32x16_bf16 v[128:143], v[6:9], v[144:147], v[128:143]
	v_mfma_f32_32x32x16_bf16 v[96:111], v[2:5], v[144:147], v[96:111]
	ds_read_b64_tr_b16 v[168:169], v0 offset:0x2600
	ds_read_b64_tr_b16 v[170:171], v0 offset:0x2700
	s_waitcnt lgkmcnt(10)
	v_mfma_f32_32x32x16_bf16 v[128:143], v[208:211], v[148:151], v[128:143]
	v_mfma_f32_32x32x16_bf16 v[96:111], v[10:13], v[148:151], v[96:111]
	ds_read_b64_tr_b16 v[172:173], v0 offset:0x3600
	ds_read_b64_tr_b16 v[174:175], v0 offset:0x3700
	s_waitcnt lgkmcnt(10)
	v_mfma_f32_32x32x16_bf16 v[112:127], v[6:9], v[152:155], v[112:127]
	v_mfma_f32_32x32x16_bf16 v[80:95], v[2:5], v[152:155], v[80:95]
	s_waitcnt lgkmcnt(8)
	v_mfma_f32_32x32x16_bf16 v[112:127], v[208:211], v[156:159], v[112:127]
	v_mfma_f32_32x32x16_bf16 v[80:95], v[10:13], v[156:159], v[80:95]
	s_waitcnt lgkmcnt(6)
	v_mfma_f32_32x32x16_bf16 v[64:79], v[6:9], v[160:163], v[64:79]
	v_mfma_f32_32x32x16_bf16 v[48:63], v[2:5], v[160:163], v[48:63]
	s_waitcnt lgkmcnt(4)
	v_mfma_f32_32x32x16_bf16 v[64:79], v[208:211], v[164:167], v[64:79]
	v_mfma_f32_32x32x16_bf16 v[48:63], v[10:13], v[164:167], v[48:63]
	s_waitcnt lgkmcnt(2)
	v_mfma_f32_32x32x16_bf16 v[32:47], v[6:9], v[168:171], v[32:47]
	v_mfma_f32_32x32x16_bf16 v[16:31], v[2:5], v[168:171], v[16:31]
	s_waitcnt lgkmcnt(0)
	v_mfma_f32_32x32x16_bf16 v[32:47], v[208:211], v[172:175], v[32:47]
	v_mfma_f32_32x32x16_bf16 v[16:31], v[10:13], v[172:175], v[16:31]
.LBB0_1319:
	v_mov_b32_e32 v252, v15
	v_mov_b32_e32 v253, v14
	s_nop 1
	v_permlane32_swap_b32_e32 v15, v252
	v_permlane32_swap_b32_e32 v14, v253
	v_add_f32_e32 v15, v15, v252
	v_add_f32_e32 v14, v14, v253
	v_mov_b32_e32 v2, v228
	v_readlane_b32 s50, v249, 48
	v_bfe_u32 v9, v2, 5, 1
	v_and_b32_e32 v3, 0x3fffffc0, v2
	v_readlane_b32 s3, v249, 57
	v_readlane_b32 s10, v249, 58
	v_and_b32_e32 v0, 31, v2
	v_lshl_add_u32 v8, v3, 2, s25
	v_cmp_eq_u32_e32 vcc, 0, v9
	v_readlane_b32 s51, v249, 49
	s_and_saveexec_b64 s[8:9], vcc
	s_cbranch_execz .LBB0_1240
	v_div_scale_f32 v3, s[0:1], v15, v15, 1.0
	v_rcp_f32_e32 v4, v3
	s_nop 0
	v_fma_f32 v5, -v3, v4, 1.0
	v_fmac_f32_e32 v4, v5, v4
	v_div_scale_f32 v5, vcc, 1.0, v15, 1.0
	v_mul_f32_e32 v6, v5, v4
	v_fma_f32 v7, -v3, v6, v5
	v_fmac_f32_e32 v6, v7, v4
	v_fma_f32 v3, -v3, v6, v5
	v_div_scale_f32 v5, s[0:1], v14, v14, v229
	v_div_fmas_f32 v3, v3, v4, v6
	v_rcp_f32_e32 v6, v5
	v_div_fixup_f32 v3, v3, v15, 1.0
	v_lshl_add_u32 v4, v0, 2, v8
	v_fma_f32 v7, -v5, v6, 1.0
	v_fmac_f32_e32 v6, v7, v6
	v_div_scale_f32 v7, vcc, v229, v14, v229
	v_mul_f32_e32 v10, v7, v6
	v_fma_f32 v11, -v5, v10, v7
	v_fmac_f32_e32 v10, v11, v6
	v_fma_f32 v5, -v5, v10, v7
	v_div_fmas_f32 v5, v5, v6, v10
	v_div_fixup_f32 v5, v5, v14, v229
	ds_write2_b32 v4, v3, v5 offset1:32
	s_branch .LBB0_1240

.LBB0_2095:
	s_ashr_i32 s0, s62, 31
	s_lshr_b32 s0, s0, 26
	s_add_i32 s0, s62, s0
	s_ashr_i32 s34, s0, 6
	s_and_b32 s0, s0, 0xffffc0
	s_sub_i32 s3, s62, s0
	s_ashr_i32 s35, s34, 31
	s_mul_i32 s7, s34, 0x17000000
	s_mul_hi_i32 s6, s34, 0x17000000
	s_add_u32 s0, s38, s7
	v_mov_b32_e32 v4, v228
	s_addc_u32 s1, s39, s6
	s_lshl_b32 s63, s3, 8
	v_mov_b64_e32 v[2:3], s[0:1]
	v_and_b32_e32 v6, 31, v4
	v_ashrrev_i32_e32 v5, 6, v4
	v_or_b32_e32 v0, s63, v6
	v_lshl_add_u32 v0, v5, 5, v0
	v_bfe_u32 v7, v4, 5, 1
	v_mad_i64_i32 v[2:3], s[4:5], v0, s19, v[2:3]
	v_lshl_add_u64 v[2:3], v[2:3], 0, s[10:11]
	v_lshlrev_b32_e32 v0, 4, v7
	v_lshl_add_u64 v[2:3], v[2:3], 0, v[0:1]
	v_readfirstlane_b32 s3, v5
	v_mov_b32_e32 v5, v228
	global_load_dwordx4 v[176:179], v[2:3], off
	global_load_dwordx4 v[180:183], v[2:3], off offset:32
	global_load_dwordx4 v[184:187], v[2:3], off offset:64
	global_load_dwordx4 v[188:191], v[2:3], off offset:96
	global_load_dwordx4 v[192:195], v[2:3], off offset:128
	global_load_dwordx4 v[196:199], v[2:3], off offset:160
	global_load_dwordx4 v[200:203], v[2:3], off offset:192
	global_load_dwordx4 v[204:207], v[2:3], off offset:224
	s_barrier
	s_add_u32 s0, s0, s10
	v_and_b32_e32 v3, 0x60, v5
	v_lshlrev_b32_e32 v9, 3, v5
	v_bfe_u32 v2, v5, 2, 2
	v_and_or_b32 v9, v9, 24, v3
	v_lshrrev_b32_e32 v3, 1, v5
	v_and_b32_e32 v8, 15, v5
	v_and_or_b32 v10, v3, 8, v2
	v_ashrrev_i32_e32 v3, 4, v5
	v_bitop3_b32 v2, v3, v8, 7 bitop3:0x6c
	v_mul_lo_u32 v11, v3, s19
	v_lshl_or_b32 v2, v2, 4, v11
	v_and_b32_e32 v11, 0x7ffff0, v3
	v_lshrrev_b32_e32 v3, 1, v3
	v_and_b32_e32 v3, 4, v3
	s_addc_u32 s1, s1, s11
	v_or3_b32 v3, v11, v3, v10
	s_add_u32 s4, s0, 0x1000
	v_mul_u32_u24_e32 v3, 0x2e00, v3
	s_addc_u32 s5, s1, 0
	s_lshl_b32 s24, s3, 10
	v_or_b32_e32 v3, v3, v9
	s_add_i32 s64, s24, 0
	v_lshlrev_b32_e32 v11, 1, v3
	v_mov_b32_e32 v3, v1
	s_add_i32 s65, s64, 0x10000
	v_lshl_add_u64 v[2:3], s[0:1], 0, v[2:3]
	v_lshl_add_u64 v[2:3], v[2:3], 0, s[12:13]
	s_mov_b32 m0, s65
	v_mov_b32_e32 v14, v1
	global_load_lds_dwordx4 v[2:3], off
	v_add_u32_e32 v2, 0x200, v5
	v_ashrrev_i32_e32 v3, 4, v2
	v_bitop3_b32 v2, v3, v8, 7 bitop3:0x6c
	v_mul_lo_u32 v5, v3, s19
	v_lshl_or_b32 v2, v2, 4, v5
	v_and_b32_e32 v5, 0x7ffff0, v3
	v_lshrrev_b32_e32 v3, 1, v3
	v_and_b32_e32 v3, 4, v3
	v_or3_b32 v3, v5, v3, v10
	v_mul_u32_u24_e32 v3, 0x2e00, v3
	v_or_b32_e32 v3, v3, v9
	v_lshlrev_b32_e32 v5, 1, v3
	v_mov_b32_e32 v3, v1
	s_mov_b32 m0, s64
	v_lshl_add_u64 v[2:3], s[0:1], 0, v[2:3]
	global_load_lds_dwordx4 v11, s[4:5]
	v_lshl_add_u64 v[2:3], v[2:3], 0, s[12:13]
	s_add_i32 m0, s64, 0x12000
	v_mov_b32_e32 v15, v1
	global_load_lds_dwordx4 v[2:3], off
	s_add_i32 m0, s64, 0x2000
	v_mov_b32_e32 v2, v228
	global_load_lds_dwordx4 v5, s[4:5]
	s_cmp_lg_u32 0, -1
	v_and_b32_e32 v8, 0x60, v2
	v_lshlrev_b32_e32 v9, 3, v2
	v_bfe_u32 v5, v2, 2, 2
	v_and_or_b32 v8, v9, 24, v8
	v_lshrrev_b32_e32 v9, 1, v2
	v_and_b32_e32 v3, 15, v2
	v_and_or_b32 v5, v9, 8, v5
	v_ashrrev_i32_e32 v9, 4, v2
	s_cselect_b32 s24, 0, 0
	v_bitop3_b32 v10, v9, v3, 7 bitop3:0x6c
	v_mul_lo_u32 v11, v9, s19
	s_add_i32 s27, s24, 0x10000
	v_lshl_or_b32 v10, v10, 4, v11
	v_and_b32_e32 v11, 0x7ffff0, v9
	v_lshrrev_b32_e32 v9, 1, v9
	s_add_u32 s4, s0, 0x170800
	v_and_b32_e32 v9, 4, v9
	s_addc_u32 s5, s1, 0
	v_or3_b32 v9, v11, v9, v5
	s_add_u32 s0, s0, 0x171000
	v_mul_u32_u24_e32 v9, 0x2e00, v9
	s_addc_u32 s1, s1, 0
	s_add_i32 m0, s64, 0x14000
	s_add_i32 s33, s64, 0x4000
	v_or_b32_e32 v9, v9, v8
	v_add_u32_e32 v2, 0x200, v2
	v_lshlrev_b32_e32 v9, 1, v9
	global_load_lds_dwordx4 v10, s[4:5]
	s_mov_b32 m0, s33
	v_ashrrev_i32_e32 v2, 4, v2
	global_load_lds_dwordx4 v9, s[0:1]
	v_bitop3_b32 v3, v2, v3, 7 bitop3:0x6c
	v_mul_lo_u32 v9, v2, s19
	v_lshl_or_b32 v3, v3, 4, v9
	v_and_b32_e32 v9, 0x7ffff0, v2
	v_lshrrev_b32_e32 v2, 1, v2
	v_and_b32_e32 v2, 4, v2
	v_or3_b32 v2, v9, v2, v5
	v_mul_u32_u24_e32 v2, 0x2e00, v2
	v_or_b32_e32 v2, v2, v8
	s_add_i32 m0, s64, 0x16000
	v_lshlrev_b32_e32 v2, 1, v2
	global_load_lds_dwordx4 v3, s[4:5]
	s_add_i32 m0, s64, 0x6000
	v_and_b32_e32 v3, 63, v4
	global_load_lds_dwordx4 v2, s[0:1]
	v_lshlrev_b32_e32 v8, 4, v4
	v_lshlrev_b32_e32 v5, 3, v3
	v_and_b32_e32 v8, 0xc0, v8
	v_lshlrev_b32_e32 v9, 1, v4
	v_and_b32_e32 v2, 0x3fffffc0, v4
	v_and_or_b32 v8, v5, 24, v8
	v_and_b32_e32 v9, 32, v9
	v_and_b32_e32 v5, 0x100, v5
	v_lshlrev_b32_e32 v5, 3, v5
	v_bitop3_b32 v4, v7, v4, 7 bitop3:0x78
	s_cmp_gt_i32 s3, 3
	v_lshl_add_u32 v2, v2, 2, s18
	v_or3_b32 v232, v8, v9, v5
	v_lshlrev_b32_e32 v5, 8, v6
	v_lshlrev_b32_e32 v4, 4, v4
	s_cselect_b64 s[42:43], -1, 0
	s_cmp_lt_i32 s3, 4
	v_add3_u32 v233, v5, s27, v4
	s_cselect_b64 s[52:53], -1, 0
	v_cmp_gt_u32_e64 s[4:5], 32, v3
	v_lshl_add_u32 v235, v6, 2, v2
	v_add_u32_e32 v236, v2, v0
	s_add_u32 s66, s8, s7
	v_mov_b32_e32 v0, v1
	v_mov_b32_e32 v2, v1
	v_mov_b32_e32 v3, v1
	v_mov_b32_e32 v4, v1
	v_mov_b32_e32 v5, v1
	v_mov_b32_e32 v6, v1
	v_mov_b32_e32 v7, v1
	v_mov_b32_e32 v8, v1
	v_mov_b32_e32 v9, v1
	v_mov_b32_e32 v10, v1
	v_mov_b32_e32 v11, v1
	v_mov_b32_e32 v12, v1
	v_mov_b32_e32 v13, v1
	v_mov_b64_e32 v[110:111], v[14:15]
	v_mov_b64_e32 v[94:95], v[14:15]
	v_mov_b64_e32 v[46:47], v[14:15]
	v_mov_b64_e32 v[30:31], v[14:15]
	v_mov_b64_e32 v[142:143], v[14:15]
	v_mov_b64_e32 v[126:127], v[14:15]
	v_mov_b64_e32 v[78:79], v[14:15]
	v_mov_b64_e32 v[62:63], v[14:15]
	v_add_u32_e32 v234, s24, v232
	s_addc_u32 s67, s9, s6
	s_mov_b64 s[58:59], 0
	s_xor_b64 s[60:61], s[42:43], -1
	s_mov_b32 s68, 0
	v_mov_b64_e32 v[108:109], v[12:13]
	v_mov_b64_e32 v[106:107], v[10:11]
	v_mov_b64_e32 v[104:105], v[8:9]
	v_mov_b64_e32 v[102:103], v[6:7]
	v_mov_b64_e32 v[100:101], v[4:5]
	v_mov_b64_e32 v[98:99], v[2:3]
	v_mov_b64_e32 v[96:97], v[0:1]
	v_mov_b64_e32 v[92:93], v[12:13]
	v_mov_b64_e32 v[90:91], v[10:11]
	v_mov_b64_e32 v[88:89], v[8:9]
	v_mov_b64_e32 v[86:87], v[6:7]
	v_mov_b64_e32 v[84:85], v[4:5]
	v_mov_b64_e32 v[82:83], v[2:3]
	v_mov_b64_e32 v[80:81], v[0:1]
	v_mov_b64_e32 v[44:45], v[12:13]
	v_mov_b64_e32 v[42:43], v[10:11]
	v_mov_b64_e32 v[40:41], v[8:9]
	v_mov_b64_e32 v[38:39], v[6:7]
	v_mov_b64_e32 v[36:37], v[4:5]
	v_mov_b64_e32 v[34:35], v[2:3]
	v_mov_b64_e32 v[32:33], v[0:1]
	v_mov_b64_e32 v[28:29], v[12:13]
	v_mov_b64_e32 v[26:27], v[10:11]
	v_mov_b64_e32 v[24:25], v[8:9]
	v_mov_b64_e32 v[22:23], v[6:7]
	v_mov_b64_e32 v[20:21], v[4:5]
	v_mov_b64_e32 v[18:19], v[2:3]
	v_mov_b64_e32 v[16:17], v[0:1]
	v_mov_b64_e32 v[140:141], v[12:13]
	v_mov_b64_e32 v[138:139], v[10:11]
	v_mov_b64_e32 v[136:137], v[8:9]
	v_mov_b64_e32 v[134:135], v[6:7]
	v_mov_b64_e32 v[132:133], v[4:5]
	v_mov_b64_e32 v[130:131], v[2:3]
	v_mov_b64_e32 v[128:129], v[0:1]
	v_mov_b64_e32 v[124:125], v[12:13]
	v_mov_b64_e32 v[122:123], v[10:11]
	v_mov_b64_e32 v[120:121], v[8:9]
	v_mov_b64_e32 v[118:119], v[6:7]
	v_mov_b64_e32 v[116:117], v[4:5]
	v_mov_b64_e32 v[114:115], v[2:3]
	v_mov_b64_e32 v[112:113], v[0:1]
	v_mov_b64_e32 v[76:77], v[12:13]
	v_mov_b64_e32 v[74:75], v[10:11]
	v_mov_b64_e32 v[72:73], v[8:9]
	v_mov_b64_e32 v[70:71], v[6:7]
	v_mov_b64_e32 v[68:69], v[4:5]
	v_mov_b64_e32 v[66:67], v[2:3]
	v_mov_b64_e32 v[64:65], v[0:1]
	v_mov_b64_e32 v[60:61], v[12:13]
	v_mov_b64_e32 v[58:59], v[10:11]
	v_mov_b64_e32 v[56:57], v[8:9]
	v_mov_b64_e32 v[54:55], v[6:7]
	v_mov_b64_e32 v[52:53], v[4:5]
	v_mov_b64_e32 v[50:51], v[2:3]
	v_mov_b64_e32 v[48:49], v[0:1]
	s_mov_b32 s69, 0
	v_mov_b32_e32 v237, v1
	v_mov_b32_e32 v238, v1
	v_mov_b32_e32 v208, v1
	v_mov_b32_e32 v209, v1
	v_mov_b32_e32 v210, v1
	v_mov_b32_e32 v211, v1
	v_lshrrev_b32_e32 v250, 4, v228
	v_and_b32_e32 v251, 15, v228
	v_and_b32_e32 v252, 7, v250
	v_xor_b32_e32 v251, v251, v252
	v_mul_u32_u24_e32 v250, 0x5c00, v250
	v_lshl_or_b32 v250, v251, 4, v250
	v_bfe_u32 v251, v228, 2, 2
	v_bfe_u32 v252, v228, 7, 1
	v_lshl_or_b32 v251, v252, 2, v251
	v_bfe_u32 v252, v228, 4, 1
	v_lshl_or_b32 v251, v252, 3, v251
	v_bfe_u32 v252, v228, 8, 1
	v_lshl_or_b32 v251, v252, 4, v251
	v_mul_u32_u24_e32 v251, 0x5c00, v251
	v_bfe_u32 v252, v228, 5, 2
	v_lshl_or_b32 v251, v252, 6, v251
	v_and_b32_e32 v252, 3, v228
	v_lshl_or_b32 v251, v252, 4, v251
	s_waitcnt vmcnt(0)
	s_branch .LBB0_2097

.LBB0_2101:
	s_barrier
	s_cmpk_gt_u32 s69, 0xfd
	s_cbranch_scc1 .LBB0_2103
	s_add_i32 s3, s68, 0x8000
	s_and_b32 s3, s3, 0xc000
	s_add_u32 s0, s66, s58
	s_addc_u32 s1, s67, s59
	s_add_u32 s6, s0, s16
	s_addc_u32 s7, s1, s17
	s_add_u32 s0, s0, s14
	s_addc_u32 s1, s1, s15
	s_add_i32 m0, s65, s3
	s_nop 0
	global_load_lds_dwordx4 v250, s[0:1]
	s_add_i32 m0, s64, s3
	s_add_i32 s3, s3, 0x2000
	global_load_lds_dwordx4 v251, s[6:7]
	s_add_u32 s0, s0, 0xb8000
	s_addc_u32 s1, s1, 0
	s_add_i32 m0, s65, s3
	s_add_u32 s6, s6, 0xb8000
	s_addc_u32 s7, s7, 0
	global_load_lds_dwordx4 v250, s[0:1]
	s_add_i32 m0, s64, s3
	s_nop 0
	global_load_lds_dwordx4 v251, s[6:7]
.LBB0_2103:
	s_cmp_eq_u32 s58, 0
	s_cselect_b64 s[0:1], -1, 0
	s_or_b64 s[0:1], s[60:61], s[0:1]
	s_and_b64 vcc, exec, s[0:1]
	s_cbranch_vccnz .LBB0_2105
	s_add_i32 s0, s68, 0xc000
	s_and_b32 s0, s0, 0xc000
	v_add_u32_e32 v0, s0, v234
	ds_read_b64_tr_b16 v[144:145], v0 offset:0x2000
	ds_read_b64_tr_b16 v[146:147], v0 offset:0x2100
	ds_read_b64_tr_b16 v[148:149], v0 offset:0x3000
	ds_read_b64_tr_b16 v[150:151], v0 offset:0x3100
	ds_read_b64_tr_b16 v[152:153], v0 offset:0x2200
	ds_read_b64_tr_b16 v[154:155], v0 offset:0x2300
	ds_read_b64_tr_b16 v[156:157], v0 offset:0x3200
	ds_read_b64_tr_b16 v[158:159], v0 offset:0x3300
	ds_read_b64_tr_b16 v[160:161], v0 offset:0x2400
	ds_read_b64_tr_b16 v[162:163], v0 offset:0x2500
	ds_read_b64_tr_b16 v[164:165], v0 offset:0x3400
	ds_read_b64_tr_b16 v[166:167], v0 offset:0x3500
	s_waitcnt lgkmcnt(10)
	s_nop 0
	v_mfma_f32_32x32x16_bf16 v[128:143], v[6:9], v[144:147], v[128:143]
	v_mfma_f32_32x32x16_bf16 v[96:111], v[2:5], v[144:147], v[96:111]
	ds_read_b64_tr_b16 v[168:169], v0 offset:0x2600
	ds_read_b64_tr_b16 v[170:171], v0 offset:0x2700
	s_waitcnt lgkmcnt(10)
	v_mfma_f32_32x32x16_bf16 v[128:143], v[208:211], v[148:151], v[128:143]
	v_mfma_f32_32x32x16_bf16 v[96:111], v[10:13], v[148:151], v[96:111]
	ds_read_b64_tr_b16 v[172:173], v0 offset:0x3600
	ds_read_b64_tr_b16 v[174:175], v0 offset:0x3700
	s_waitcnt lgkmcnt(10)
	v_mfma_f32_32x32x16_bf16 v[112:127], v[6:9], v[152:155], v[112:127]
	v_mfma_f32_32x32x16_bf16 v[80:95], v[2:5], v[152:155], v[80:95]
	s_waitcnt lgkmcnt(8)
	v_mfma_f32_32x32x16_bf16 v[112:127], v[208:211], v[156:159], v[112:127]
	v_mfma_f32_32x32x16_bf16 v[80:95], v[10:13], v[156:159], v[80:95]
	s_waitcnt lgkmcnt(6)
	v_mfma_f32_32x32x16_bf16 v[64:79], v[6:9], v[160:163], v[64:79]
	v_mfma_f32_32x32x16_bf16 v[32:47], v[2:5], v[160:163], v[32:47]
	s_waitcnt lgkmcnt(4)
	v_mfma_f32_32x32x16_bf16 v[64:79], v[208:211], v[164:167], v[64:79]
	v_mfma_f32_32x32x16_bf16 v[32:47], v[10:13], v[164:167], v[32:47]
	s_waitcnt lgkmcnt(2)
	v_mfma_f32_32x32x16_bf16 v[48:63], v[6:9], v[168:171], v[48:63]
	v_mfma_f32_32x32x16_bf16 v[16:31], v[2:5], v[168:171], v[16:31]
	s_waitcnt lgkmcnt(0)
	v_mfma_f32_32x32x16_bf16 v[48:63], v[208:211], v[172:175], v[48:63]
	v_mfma_f32_32x32x16_bf16 v[16:31], v[10:13], v[172:175], v[16:31]

.LBB0_2108:
	v_exp_f32_e32 v159, v175
	v_pk_add_f32 v[160:161], v[144:145], v[146:147]
	v_pk_add_f32 v[162:163], v[148:149], v[150:151]
	v_pk_add_f32 v[160:161], v[152:153], v[160:161]
	v_pk_add_f32 v[162:163], v[154:155], v[162:163]
	v_pk_add_f32 v[160:161], v[156:157], v[160:161]
	v_pk_add_f32 v[162:163], v[158:159], v[162:163]
	s_nop 0
	v_pk_add_f32 v[160:161], v[160:161], v[162:163]
	s_nop 0
	v_pk_add_f32 v[160:161], v[160:161], v[160:161] op_sel:[0,1] op_sel_hi:[1,0]
	s_nop 0
	v_cmp_lt_f32_e32 vcc, s48, v160
	v_cmp_gt_f32_e64 s[6:7], s49, v160
	s_and_b64 s[0:1], vcc, s[6:7]
	s_cmp_lg_u64 s[0:1], exec
	s_cselect_b64 vcc, -1, 0
	s_cbranch_vccnz .LBB0_2110
	v_cvt_pk_bf16_f32 v216, v144, v145
	v_cvt_pk_bf16_f32 v217, v146, v147
	v_cvt_pk_bf16_f32 v218, v148, v149
	v_cvt_pk_bf16_f32 v219, v150, v151
	v_cvt_pk_bf16_f32 v224, v152, v153
	v_cvt_pk_bf16_f32 v225, v154, v155
	v_cvt_pk_bf16_f32 v226, v156, v157
	v_cvt_pk_bf16_f32 v227, v158, v159
	v_add_f32_e32 v15, v15, v160

.LBB0_2114:
	v_exp_f32_e32 v159, v175
	v_pk_add_f32 v[160:161], v[144:145], v[146:147]
	v_pk_add_f32 v[162:163], v[148:149], v[150:151]
	v_pk_add_f32 v[160:161], v[152:153], v[160:161]
	v_pk_add_f32 v[162:163], v[154:155], v[162:163]
	v_pk_add_f32 v[160:161], v[156:157], v[160:161]
	v_pk_add_f32 v[162:163], v[158:159], v[162:163]
	s_nop 0
	v_pk_add_f32 v[160:161], v[160:161], v[162:163]
	s_nop 0
	v_pk_add_f32 v[160:161], v[160:161], v[160:161] op_sel:[0,1] op_sel_hi:[1,0]
	s_nop 0
	v_cmp_lt_f32_e32 vcc, s48, v160
	v_cmp_gt_f32_e64 s[6:7], s49, v160
	s_and_b64 s[0:1], vcc, s[6:7]
	s_cmp_lg_u64 s[0:1], exec
	s_cselect_b64 vcc, -1, 0
	s_cbranch_vccnz .LBB0_2116
	v_cvt_pk_bf16_f32 v212, v144, v145
	v_cvt_pk_bf16_f32 v213, v146, v147
	v_cvt_pk_bf16_f32 v214, v148, v149
	v_cvt_pk_bf16_f32 v215, v150, v151
	v_cvt_pk_bf16_f32 v220, v152, v153
	v_cvt_pk_bf16_f32 v221, v154, v155
	v_cvt_pk_bf16_f32 v222, v156, v157
	v_cvt_pk_bf16_f32 v223, v158, v159
	v_add_f32_e32 v14, v14, v160

.LBB0_2121:
	v_add_u32_e32 v242, s27, v234
	ds_read_b64_tr_b16 v[144:145], v242 offset:0x0
	ds_read_b64_tr_b16 v[146:147], v242 offset:0x100
	ds_read_b64_tr_b16 v[148:149], v242 offset:0x1000
	ds_read_b64_tr_b16 v[150:151], v242 offset:0x1100
	ds_read_b64_tr_b16 v[152:153], v242 offset:0x200
	ds_read_b64_tr_b16 v[154:155], v242 offset:0x300
	ds_read_b64_tr_b16 v[156:157], v242 offset:0x1200
	ds_read_b64_tr_b16 v[158:159], v242 offset:0x1300
	ds_read_b64_tr_b16 v[160:161], v242 offset:0x400
	ds_read_b64_tr_b16 v[162:163], v242 offset:0x500
	ds_read_b64_tr_b16 v[164:165], v242 offset:0x1400
	ds_read_b64_tr_b16 v[166:167], v242 offset:0x1500
	s_waitcnt lgkmcnt(10)
	s_nop 0
	v_mfma_f32_32x32x16_bf16 v[128:143], v[216:219], v[144:147], v[128:143]
	v_mfma_f32_32x32x16_bf16 v[96:111], v[212:215], v[144:147], v[96:111]
	ds_read_b64_tr_b16 v[168:169], v242 offset:0x600
	ds_read_b64_tr_b16 v[170:171], v242 offset:0x700
	s_waitcnt lgkmcnt(10)
	v_mfma_f32_32x32x16_bf16 v[128:143], v[224:227], v[148:151], v[128:143]
	v_mfma_f32_32x32x16_bf16 v[96:111], v[220:223], v[148:151], v[96:111]
	ds_read_b64_tr_b16 v[172:173], v242 offset:0x1600
	ds_read_b64_tr_b16 v[174:175], v242 offset:0x1700
	s_waitcnt lgkmcnt(10)
	v_mfma_f32_32x32x16_bf16 v[112:127], v[216:219], v[152:155], v[112:127]
	v_mfma_f32_32x32x16_bf16 v[80:95], v[212:215], v[152:155], v[80:95]
	s_waitcnt lgkmcnt(8)
	v_mfma_f32_32x32x16_bf16 v[112:127], v[224:227], v[156:159], v[112:127]
	v_mfma_f32_32x32x16_bf16 v[80:95], v[220:223], v[156:159], v[80:95]
	ds_read_b128 v[144:147], v241 offset:0x2000
	ds_read_b128 v[148:151], v240 offset:0x2000
	ds_read_b128 v[156:159], v239 offset:0x2000
	ds_read_b128 v[244:247], v0 offset:0x2000
	s_waitcnt lgkmcnt(10)
	v_mfma_f32_32x32x16_bf16 v[64:79], v[216:219], v[160:163], v[64:79]
	v_mfma_f32_32x32x16_bf16 v[32:47], v[212:215], v[160:163], v[32:47]
	s_waitcnt lgkmcnt(8)
	v_mfma_f32_32x32x16_bf16 v[64:79], v[224:227], v[164:167], v[64:79]
	v_mfma_f32_32x32x16_bf16 v[32:47], v[220:223], v[164:167], v[32:47]
	s_waitcnt lgkmcnt(6)
	v_mfma_f32_32x32x16_bf16 v[48:63], v[216:219], v[168:171], v[48:63]
	v_mfma_f32_32x32x16_bf16 v[16:31], v[212:215], v[168:171], v[16:31]
	s_waitcnt lgkmcnt(4)
	v_mfma_f32_32x32x16_bf16 v[48:63], v[224:227], v[172:175], v[48:63]
	v_mfma_f32_32x32x16_bf16 v[16:31], v[220:223], v[172:175], v[16:31]
	s_waitcnt lgkmcnt(0)
	v_mfma_f32_32x32x16_bf16 v[160:175], v[144:147], v[176:179], 0
	v_cmp_eq_f32_e32 vcc, 0, v238
	s_cmp_eq_u64 vcc, exec
	v_mfma_f32_32x32x16_bf16 v[160:175], v[148:151], v[180:183], v[160:175]
	v_mfma_f32_32x32x16_bf16 v[160:175], v[156:159], v[184:187], v[160:175]
	v_mfma_f32_32x32x16_bf16 v[160:175], v[244:247], v[188:191], v[160:175]
	s_cbranch_scc0 .LBB0_2151

.LBB0_2124:
	v_exp_f32_e32 v159, v175
	v_pk_add_f32 v[160:161], v[144:145], v[146:147]
	v_pk_add_f32 v[162:163], v[148:149], v[150:151]
	v_pk_add_f32 v[160:161], v[152:153], v[160:161]
	v_pk_add_f32 v[162:163], v[154:155], v[162:163]
	v_pk_add_f32 v[160:161], v[156:157], v[160:161]
	v_pk_add_f32 v[162:163], v[158:159], v[162:163]
	s_nop 0
	v_pk_add_f32 v[160:161], v[160:161], v[162:163]
	s_nop 0
	v_pk_add_f32 v[160:161], v[160:161], v[160:161] op_sel:[0,1] op_sel_hi:[1,0]
	s_nop 0
	v_cmp_lt_f32_e32 vcc, s48, v160
	v_cmp_gt_f32_e64 s[6:7], s49, v160
	s_and_b64 s[0:1], vcc, s[6:7]
	s_cmp_lg_u64 s[0:1], exec
	s_cselect_b64 vcc, -1, 0
	s_cbranch_vccnz .LBB0_2126
	v_cvt_pk_bf16_f32 v6, v144, v145
	v_cvt_pk_bf16_f32 v7, v146, v147
	v_cvt_pk_bf16_f32 v8, v148, v149
	v_cvt_pk_bf16_f32 v9, v150, v151
	v_cvt_pk_bf16_f32 v208, v152, v153
	v_cvt_pk_bf16_f32 v209, v154, v155
	v_cvt_pk_bf16_f32 v210, v156, v157
	v_cvt_pk_bf16_f32 v211, v158, v159
	v_add_f32_e32 v15, v15, v160

.LBB0_2130:
	v_exp_f32_e32 v159, v175
	v_pk_add_f32 v[160:161], v[144:145], v[146:147]
	v_pk_add_f32 v[162:163], v[148:149], v[150:151]
	v_pk_add_f32 v[160:161], v[152:153], v[160:161]
	v_pk_add_f32 v[162:163], v[154:155], v[162:163]
	v_pk_add_f32 v[160:161], v[156:157], v[160:161]
	v_pk_add_f32 v[162:163], v[158:159], v[162:163]
	s_nop 0
	v_pk_add_f32 v[160:161], v[160:161], v[162:163]
	s_nop 0
	v_pk_add_f32 v[160:161], v[160:161], v[160:161] op_sel:[0,1] op_sel_hi:[1,0]
	s_nop 0
	v_cmp_lt_f32_e32 vcc, s48, v160
	v_cmp_gt_f32_e64 s[6:7], s49, v160
	s_and_b64 s[0:1], vcc, s[6:7]
	s_cmp_lg_u64 s[0:1], exec
	s_cselect_b64 vcc, -1, 0
	s_cbranch_vccnz .LBB0_2132
	v_cvt_pk_bf16_f32 v2, v144, v145
	v_cvt_pk_bf16_f32 v3, v146, v147
	v_cvt_pk_bf16_f32 v4, v148, v149
	v_cvt_pk_bf16_f32 v5, v150, v151
	v_cvt_pk_bf16_f32 v10, v152, v153
	v_cvt_pk_bf16_f32 v11, v154, v155
	v_cvt_pk_bf16_f32 v12, v156, v157
	v_cvt_pk_bf16_f32 v13, v158, v159
	v_add_f32_e32 v14, v14, v160

.LBB0_2137:
	s_andn2_b64 vcc, exec, s[52:53]
	s_cbranch_vccnz .LBB0_2096
	ds_read_b64_tr_b16 v[144:145], v242 offset:0x2000
	ds_read_b64_tr_b16 v[146:147], v242 offset:0x2100
	ds_read_b64_tr_b16 v[148:149], v242 offset:0x3000
	ds_read_b64_tr_b16 v[150:151], v242 offset:0x3100
	ds_read_b64_tr_b16 v[152:153], v242 offset:0x2200
	ds_read_b64_tr_b16 v[154:155], v242 offset:0x2300
	ds_read_b64_tr_b16 v[156:157], v242 offset:0x3200
	ds_read_b64_tr_b16 v[158:159], v242 offset:0x3300
	ds_read_b64_tr_b16 v[160:161], v242 offset:0x2400
	ds_read_b64_tr_b16 v[162:163], v242 offset:0x2500
	ds_read_b64_tr_b16 v[164:165], v242 offset:0x3400
	ds_read_b64_tr_b16 v[166:167], v242 offset:0x3500
	s_waitcnt lgkmcnt(10)
	s_nop 0
	v_mfma_f32_32x32x16_bf16 v[128:143], v[6:9], v[144:147], v[128:143]
	v_mfma_f32_32x32x16_bf16 v[96:111], v[2:5], v[144:147], v[96:111]
	ds_read_b64_tr_b16 v[168:169], v242 offset:0x2600
	ds_read_b64_tr_b16 v[170:171], v242 offset:0x2700
	s_waitcnt lgkmcnt(10)
	v_mfma_f32_32x32x16_bf16 v[128:143], v[208:211], v[148:151], v[128:143]
	v_mfma_f32_32x32x16_bf16 v[96:111], v[10:13], v[148:151], v[96:111]
	ds_read_b64_tr_b16 v[172:173], v242 offset:0x3600
	ds_read_b64_tr_b16 v[174:175], v242 offset:0x3700
	s_waitcnt lgkmcnt(10)
	v_mfma_f32_32x32x16_bf16 v[112:127], v[6:9], v[152:155], v[112:127]
	v_mfma_f32_32x32x16_bf16 v[80:95], v[2:5], v[152:155], v[80:95]
	s_waitcnt lgkmcnt(8)
	v_mfma_f32_32x32x16_bf16 v[112:127], v[208:211], v[156:159], v[112:127]
	v_mfma_f32_32x32x16_bf16 v[80:95], v[10:13], v[156:159], v[80:95]
	s_waitcnt lgkmcnt(6)
	v_mfma_f32_32x32x16_bf16 v[64:79], v[6:9], v[160:163], v[64:79]
	v_mfma_f32_32x32x16_bf16 v[32:47], v[2:5], v[160:163], v[32:47]
	s_waitcnt lgkmcnt(4)
	v_mfma_f32_32x32x16_bf16 v[64:79], v[208:211], v[164:167], v[64:79]
	v_mfma_f32_32x32x16_bf16 v[32:47], v[10:13], v[164:167], v[32:47]
	s_waitcnt lgkmcnt(2)
	v_mfma_f32_32x32x16_bf16 v[48:63], v[6:9], v[168:171], v[48:63]
	v_mfma_f32_32x32x16_bf16 v[16:31], v[2:5], v[168:171], v[16:31]
	s_waitcnt lgkmcnt(0)
	v_mfma_f32_32x32x16_bf16 v[48:63], v[208:211], v[172:175], v[48:63]
	v_mfma_f32_32x32x16_bf16 v[16:31], v[10:13], v[172:175], v[16:31]
	s_branch .LBB0_2096

.LBB0_2150:
	v_add_f32_e32 v160, 0, v144
	v_add_f32_e32 v160, v145, v160
	v_add_f32_e32 v160, v146, v160
	v_add_f32_e32 v160, v147, v160
	v_add_f32_e32 v160, v148, v160
	v_add_f32_e32 v160, v149, v160
	v_add_f32_e32 v160, v150, v160
	v_add_f32_e32 v160, v151, v160
	v_add_f32_e32 v160, v152, v160
	v_add_f32_e32 v160, v153, v160
	v_add_f32_e32 v160, v154, v160
	v_exp_f32_e32 v159, v159
	v_add_f32_e32 v160, v155, v160
	v_add_f32_e32 v160, v156, v160
	v_add_f32_e32 v160, v157, v160
	v_add_f32_e32 v160, v158, v160
	v_add_f32_e32 v160, v159, v160
	v_fmac_f32_e32 v160, v14, v243
	v_cvt_pk_bf16_f32 v212, v144, v145
	v_cvt_pk_bf16_f32 v213, v146, v147
	v_cvt_pk_bf16_f32 v214, v148, v149
	v_cvt_pk_bf16_f32 v215, v150, v151
	v_cvt_pk_bf16_f32 v220, v152, v153
	v_cvt_pk_bf16_f32 v221, v154, v155
	v_cvt_pk_bf16_f32 v222, v156, v157
	v_cvt_pk_bf16_f32 v223, v158, v159
	s_nop 0
	v_mov_b32_e32 v14, v160
	v_cmp_neq_f32_e32 vcc, 1.0, v242
	v_cmp_neq_f32_e64 s[6:7], 1.0, v243
	s_or_b64 vcc, vcc, s[6:7]
	s_cbranch_vccnz .LBB0_2118
	s_branch .LBB0_2121

.LBB0_2162:
	v_add_f32_e32 v2, 0, v144
	v_add_f32_e32 v2, v145, v2
	v_add_f32_e32 v2, v146, v2
	v_add_f32_e32 v2, v147, v2
	v_add_f32_e32 v2, v148, v2
	v_add_f32_e32 v2, v149, v2
	v_add_f32_e32 v2, v150, v2
	v_add_f32_e32 v2, v151, v2
	v_add_f32_e32 v2, v152, v2
	v_add_f32_e32 v2, v153, v2
	v_add_f32_e32 v2, v154, v2
	v_exp_f32_e32 v0, v0
	v_add_f32_e32 v2, v155, v2
	v_add_f32_e32 v2, v156, v2
	v_add_f32_e32 v2, v157, v2
	v_add_f32_e32 v2, v158, v2
	v_add_f32_e32 v2, v0, v2
	v_mov_b32_e32 v159, v2
	v_fmac_f32_e32 v159, v14, v244
	v_cvt_pk_bf16_f32 v2, v144, v145
	v_cvt_pk_bf16_f32 v3, v146, v147
	v_cvt_pk_bf16_f32 v4, v148, v149
	v_cvt_pk_bf16_f32 v5, v150, v151
	v_cvt_pk_bf16_f32 v10, v152, v153
	v_cvt_pk_bf16_f32 v11, v154, v155
	v_cvt_pk_bf16_f32 v12, v156, v157
	v_cvt_pk_bf16_f32 v13, v158, v0
	s_nop 0
	v_mov_b32_e32 v14, v159
	v_cmp_neq_f32_e32 vcc, 1.0, v243
	v_cmp_neq_f32_e64 s[6:7], 1.0, v244
	s_or_b64 vcc, vcc, s[6:7]
	s_cbranch_vccnz .LBB0_2134
	s_branch .LBB0_2137

.LBB0_2171:
	s_and_b64 vcc, exec, s[42:43]
	s_cbranch_vccz .LBB0_2173
	s_cmp_lg_u32 0, -1
	s_cselect_b32 s0, 0, 0
	s_add_i32 s0, s0, 0xc000
	v_add_u32_e32 v0, s0, v232
	ds_read_b64_tr_b16 v[144:145], v0 offset:0x2000
	ds_read_b64_tr_b16 v[146:147], v0 offset:0x2100
	ds_read_b64_tr_b16 v[148:149], v0 offset:0x3000
	ds_read_b64_tr_b16 v[150:151], v0 offset:0x3100
	ds_read_b64_tr_b16 v[152:153], v0 offset:0x2200
	ds_read_b64_tr_b16 v[154:155], v0 offset:0x2300
	ds_read_b64_tr_b16 v[156:157], v0 offset:0x3200
	ds_read_b64_tr_b16 v[158:159], v0 offset:0x3300
	ds_read_b64_tr_b16 v[160:161], v0 offset:0x2400
	ds_read_b64_tr_b16 v[162:163], v0 offset:0x2500
	ds_read_b64_tr_b16 v[164:165], v0 offset:0x3400
	ds_read_b64_tr_b16 v[166:167], v0 offset:0x3500
	s_waitcnt lgkmcnt(10)
	s_nop 0
	v_mfma_f32_32x32x16_bf16 v[128:143], v[6:9], v[144:147], v[128:143]
	v_mfma_f32_32x32x16_bf16 v[96:111], v[2:5], v[144:147], v[96:111]
	ds_read_b64_tr_b16 v[168:169], v0 offset:0x2600
	ds_read_b64_tr_b16 v[170:171], v0 offset:0x2700
	s_waitcnt lgkmcnt(10)
	v_mfma_f32_32x32x16_bf16 v[128:143], v[208:211], v[148:151], v[128:143]
	v_mfma_f32_32x32x16_bf16 v[96:111], v[10:13], v[148:151], v[96:111]
	ds_read_b64_tr_b16 v[172:173], v0 offset:0x3600
	ds_read_b64_tr_b16 v[174:175], v0 offset:0x3700
	s_waitcnt lgkmcnt(10)
	v_mfma_f32_32x32x16_bf16 v[112:127], v[6:9], v[152:155], v[112:127]
	v_mfma_f32_32x32x16_bf16 v[80:95], v[2:5], v[152:155], v[80:95]
	s_waitcnt lgkmcnt(8)
	v_mfma_f32_32x32x16_bf16 v[112:127], v[208:211], v[156:159], v[112:127]
	v_mfma_f32_32x32x16_bf16 v[80:95], v[10:13], v[156:159], v[80:95]
	s_waitcnt lgkmcnt(6)
	v_mfma_f32_32x32x16_bf16 v[64:79], v[6:9], v[160:163], v[64:79]
	v_mfma_f32_32x32x16_bf16 v[32:47], v[2:5], v[160:163], v[32:47]
	s_waitcnt lgkmcnt(4)
	v_mfma_f32_32x32x16_bf16 v[64:79], v[208:211], v[164:167], v[64:79]
	v_mfma_f32_32x32x16_bf16 v[32:47], v[10:13], v[164:167], v[32:47]
	s_waitcnt lgkmcnt(2)
	v_mfma_f32_32x32x16_bf16 v[48:63], v[6:9], v[168:171], v[48:63]
	v_mfma_f32_32x32x16_bf16 v[16:31], v[2:5], v[168:171], v[16:31]
	s_waitcnt lgkmcnt(0)
	v_mfma_f32_32x32x16_bf16 v[48:63], v[208:211], v[172:175], v[48:63]
	v_mfma_f32_32x32x16_bf16 v[16:31], v[10:13], v[172:175], v[16:31]
.LBB0_2173:
	v_mov_b32_e32 v252, v15
	v_mov_b32_e32 v253, v14
	s_nop 1
	v_permlane32_swap_b32_e32 v15, v252
	v_permlane32_swap_b32_e32 v14, v253
	v_add_f32_e32 v15, v15, v252
	v_add_f32_e32 v14, v14, v253
	v_mov_b32_e32 v2, v228
	s_nop 0
	v_bfe_u32 v5, v2, 5, 1
	v_and_b32_e32 v3, 0x3fffffc0, v2
	v_and_b32_e32 v0, 31, v2
	v_lshl_add_u32 v3, v3, 2, s18
	v_cmp_eq_u32_e32 vcc, 0, v5
	s_and_saveexec_b64 s[0:1], vcc
	s_cbranch_execz .LBB0_2094
	v_div_scale_f32 v4, s[4:5], v15, v15, 1.0
	v_rcp_f32_e32 v6, v4
	v_div_scale_f32 v7, vcc, 1.0, v15, 1.0
	v_fma_f32 v8, -v4, v6, 1.0
	v_fmac_f32_e32 v6, v8, v6
	v_mul_f32_e32 v8, v7, v6
	v_fma_f32 v9, -v4, v8, v7
	v_fmac_f32_e32 v8, v9, v6
	v_fma_f32 v4, -v4, v8, v7
	v_div_scale_f32 v7, s[4:5], v14, v14, v229
	v_rcp_f32_e32 v9, v7
	v_div_fmas_f32 v4, v4, v6, v8
	v_div_fixup_f32 v4, v4, v15, 1.0
	v_lshl_add_u32 v6, v0, 2, v3
	v_fma_f32 v8, -v7, v9, 1.0
	v_fmac_f32_e32 v9, v8, v9
	v_div_scale_f32 v8, vcc, v229, v14, v229
	v_mul_f32_e32 v10, v8, v9
	v_fma_f32 v11, -v7, v10, v8
	v_fmac_f32_e32 v10, v11, v9
	v_fma_f32 v7, -v7, v10, v8
	v_div_fmas_f32 v7, v7, v9, v10
	v_div_fixup_f32 v7, v7, v14, v229
	ds_write2_b32 v6, v4, v7 offset1:32
	s_branch .LBB0_2094

	.amdhsa_kernel _Z4mega6Params
		.amdhsa_group_segment_fixed_size 0
		.amdhsa_private_segment_fixed_size 0
		.amdhsa_kernarg_size 504
		.amdhsa_user_sgpr_count 2
		.amdhsa_user_sgpr_dispatch_ptr 0
		.amdhsa_user_sgpr_queue_ptr 0
		.amdhsa_user_sgpr_kernarg_segment_ptr 1
		.amdhsa_user_sgpr_dispatch_id 0
		.amdhsa_user_sgpr_kernarg_preload_length 0
		.amdhsa_user_sgpr_kernarg_preload_offset 0
		.amdhsa_user_sgpr_private_segment_size 0
		.amdhsa_uses_dynamic_stack 0
		.amdhsa_enable_private_segment 0
		.amdhsa_system_sgpr_workgroup_id_x 1
		.amdhsa_system_sgpr_workgroup_id_y 0
		.amdhsa_system_sgpr_workgroup_id_z 0
		.amdhsa_system_sgpr_workgroup_info 0
		.amdhsa_system_vgpr_workitem_id 2
		.amdhsa_next_free_vgpr 256
		.amdhsa_next_free_sgpr 98
		.amdhsa_accum_offset 256
		.amdhsa_reserve_vcc 1
		.amdhsa_float_round_mode_32 0
		.amdhsa_float_round_mode_16_64 0
		.amdhsa_float_denorm_mode_32 3
		.amdhsa_float_denorm_mode_16_64 3
		.amdhsa_dx10_clamp 1
		.amdhsa_ieee_mode 1
		.amdhsa_fp16_overflow 0
		.amdhsa_tg_split 0
		.amdhsa_exception_fp_ieee_invalid_op 0
		.amdhsa_exception_fp_denorm_src 0
		.amdhsa_exception_fp_ieee_div_zero 0
		.amdhsa_exception_fp_ieee_overflow 0
		.amdhsa_exception_fp_ieee_underflow 0
		.amdhsa_exception_fp_ieee_inexact 0
		.amdhsa_exception_int_div_zero 0
	.end_amdhsa_kernel

amdhsa.kernels:
  - .agpr_count:     0
    .args:
      - .offset:         0
        .size:           248
        .value_kind:     by_value
      - .offset:         248
        .size:           4
        .value_kind:     hidden_block_count_x
      - .offset:         252
        .size:           4
        .value_kind:     hidden_block_count_y
      - .offset:         256
        .size:           4
        .value_kind:     hidden_block_count_z
      - .offset:         260
        .size:           2
        .value_kind:     hidden_group_size_x
      - .offset:         262
        .size:           2
        .value_kind:     hidden_group_size_y
      - .offset:         264
        .size:           2
        .value_kind:     hidden_group_size_z
      - .offset:         266
        .size:           2
        .value_kind:     hidden_remainder_x
      - .offset:         268
        .size:           2
        .value_kind:     hidden_remainder_y
      - .offset:         270
        .size:           2
        .value_kind:     hidden_remainder_z
      - .offset:         288
        .size:           8
        .value_kind:     hidden_global_offset_x
      - .offset:         296
        .size:           8
        .value_kind:     hidden_global_offset_y
      - .offset:         304
        .size:           8
        .value_kind:     hidden_global_offset_z
      - .offset:         312
        .size:           2
        .value_kind:     hidden_grid_dims
      - .offset:         336
        .size:           8
        .value_kind:     hidden_multigrid_sync_arg
      - .offset:         368
        .size:           4
        .value_kind:     hidden_dynamic_lds_size
    .group_segment_fixed_size: 0
    .kernarg_segment_align: 8
    .kernarg_segment_size: 504
    .language:       OpenCL C
    .language_version:
      - 2
      - 0
    .max_flat_workgroup_size: 512
    .name:           _Z4mega6Params
    .private_segment_fixed_size: 0
    .sgpr_count:     104
    .sgpr_spill_count: 79
    .symbol:         _Z4mega6Params.kd
    .uniform_work_group_size: 1
    .uses_dynamic_stack: false
    .vgpr_count:     256
    .vgpr_spill_count: 0
    .wavefront_size: 64
